# norm loops pipelined, prep transpose loads batched, FoX QK fragment reads pipelined 9 deep, FoX finalize gate loads hoisted
# speedup vs baseline: 1.0286x; 1.0163x over previous
; #define LAS __attribute__((address_space(3)))
; __device__ __forceinline__ void item_fox(const Params& p, int l, int bl, int h, int qb, LAS unsigned char* lds) {
;     ...
;     auto qk_sm = [&](int kt) {
;         const int k0 = kt * 64;
;         LAS unsigned char* kb = lds + ((kt & 1) ? D_K1 : D_K0);
;         f32x16 S0, S1;
; #pragma unroll
;         for (int r = 0; r < 16; ++r) { S0[r] = 0.f; S1[r] = 0.f; }
; #pragma unroll
;         for (int ks = 0; ks < 8; ++ks) {
;             const bf16x8 a0 = *(const LAS bf16x8*)(kb + rowA * 272 + ks * 32 + hi * 16);
;             const bf16x8 a1 = *(const LAS bf16x8*)(kb + (rowA + 32) * 272 + ks * 32 + hi * 16);
;             S0 = __builtin_amdgcn_mfma_f32_32x32x16_bf16(a0, Qf[ks], S0, 0, 0, 0);
;             S1 = __builtin_amdgcn_mfma_f32_32x32x16_bf16(a1, Qf[ks], S1, 0, 0, 0);
;         }
;         const int kb0 = k0 + 8 * hi;
; #pragma unroll
;         for (int q4 = 0; q4 < 4; ++q4) {
;             const f32x4 c0 = *(const LAS f32x4*)(cumL + kb0 + (q4 & 1) * 4 + (q4 >> 1) * 16);
;             const f32x4 c1 = *(const LAS f32x4*)(cumL + kb0 + 32 + (q4 & 1) * 4 + (q4 >> 1) * 16);
; #pragma unroll
;             for (int j = 0; j < 4; ++j) { const int r = q4 * 4 + j; S0[r] = fmaf(S0[r], C2, c0[j]); S1[r] = fmaf(S1[r], C2, c1[j]); }
;         }
.LBB0_1005:
	s_bfe_i32 s0, s24, 0x10000
	s_and_b32 s0, s0, 0x4400
	v_add_u32_e32 v0, s0, v193
	ds_read_b128 v[2:5], v0 offset:8704
	ds_read_b128 v[6:9], v0
	ds_read_b128 v[10:13], v0 offset:32
	ds_read_b128 v[212:215], v0 offset:8736
	ds_read_b128 v[216:219], v0 offset:64
	ds_read_b128 v[220:223], v0 offset:8768
	ds_read_b128 v[224:227], v0 offset:96
	ds_read_b128 v[228:231], v0 offset:8800
	ds_read_b128 v[232:235], v0 offset:128
	s_add_i32 s0, s30, -1
	s_cmp_le_i32 s0, s26
	s_waitcnt lgkmcnt(8)
	v_mfma_f32_32x32x16_bf16 v[80:95], v[2:5], v[112:115], 0
	ds_read_b128 v[2:5], v0 offset:8832
	s_waitcnt lgkmcnt(8)
	v_mfma_f32_32x32x16_bf16 v[96:111], v[6:9], v[112:115], 0
	ds_read_b128 v[6:9], v0 offset:160
	s_waitcnt lgkmcnt(8)
	v_mfma_f32_32x32x16_bf16 v[96:111], v[10:13], v[116:119], v[96:111]
	ds_read_b128 v[10:13], v0 offset:8864
	s_waitcnt lgkmcnt(8)
	v_mfma_f32_32x32x16_bf16 v[80:95], v[212:215], v[116:119], v[80:95]
	ds_read_b128 v[212:215], v0 offset:192
	s_waitcnt lgkmcnt(8)
	v_mfma_f32_32x32x16_bf16 v[96:111], v[216:219], v[120:123], v[96:111]
	ds_read_b128 v[216:219], v0 offset:8896
	s_waitcnt lgkmcnt(8)
	v_mfma_f32_32x32x16_bf16 v[80:95], v[220:223], v[120:123], v[80:95]
	ds_read_b128 v[220:223], v0 offset:224
	s_waitcnt lgkmcnt(8)
	v_mfma_f32_32x32x16_bf16 v[96:111], v[224:227], v[124:127], v[96:111]
	ds_read_b128 v[224:227], v0 offset:8928
	s_waitcnt lgkmcnt(8)
	v_mfma_f32_32x32x16_bf16 v[80:95], v[228:231], v[124:127], v[80:95]
	s_waitcnt lgkmcnt(7)
	v_mfma_f32_32x32x16_bf16 v[96:111], v[232:235], v[128:131], v[96:111]
	s_waitcnt lgkmcnt(6)
	v_mfma_f32_32x32x16_bf16 v[80:95], v[2:5], v[128:131], v[80:95]
	s_waitcnt lgkmcnt(5)
	v_mfma_f32_32x32x16_bf16 v[96:111], v[6:9], v[132:135], v[96:111]
	s_waitcnt lgkmcnt(4)
	v_mfma_f32_32x32x16_bf16 v[80:95], v[10:13], v[132:135], v[80:95]
	s_waitcnt lgkmcnt(3)
	v_mfma_f32_32x32x16_bf16 v[96:111], v[212:215], v[136:139], v[96:111]
	s_waitcnt lgkmcnt(2)
	v_mfma_f32_32x32x16_bf16 v[80:95], v[216:219], v[136:139], v[80:95]
	s_waitcnt lgkmcnt(1)
	v_mfma_f32_32x32x16_bf16 v[96:111], v[220:223], v[140:143], v[96:111]
	s_waitcnt lgkmcnt(0)
	v_mfma_f32_32x32x16_bf16 v[80:95], v[224:227], v[140:143], v[80:95]
	ds_read_b128 v[212:215], v195 offset:128
	ds_read_b128 v[216:219], v195
	ds_read_b128 v[220:223], v195 offset:16
	ds_read_b128 v[224:227], v195 offset:144
	ds_read_b128 v[6:9], v195 offset:64
	ds_read_b128 v[228:231], v195 offset:192
	ds_read_b128 v[10:13], v195 offset:80
	ds_read_b128 v[232:235], v195 offset:208
	s_waitcnt lgkmcnt(5)
	s_nop 0
	v_pk_fma_f32 v[102:103], v[102:103], s[36:37], v[222:223] op_sel_hi:[1,0,1]
	s_waitcnt lgkmcnt(3)
	v_pk_fma_f32 v[8:9], v[106:107], s[36:37], v[8:9] op_sel_hi:[1,0,1]
	v_pk_fma_f32 v[100:101], v[100:101], s[36:37], v[220:221] op_sel_hi:[1,0,1]
	s_waitcnt lgkmcnt(1)
	v_pk_fma_f32 v[2:3], v[110:111], s[36:37], v[12:13] op_sel_hi:[1,0,1]
	v_pk_fma_f32 v[4:5], v[108:109], s[36:37], v[10:11] op_sel_hi:[1,0,1]
	v_pk_fma_f32 v[12:13], v[104:105], s[36:37], v[6:7] op_sel_hi:[1,0,1]
	v_pk_fma_f32 v[98:99], v[98:99], s[36:37], v[218:219] op_sel_hi:[1,0,1]
	v_pk_fma_f32 v[96:97], v[96:97], s[36:37], v[216:217] op_sel_hi:[1,0,1]
	s_waitcnt lgkmcnt(0)
	v_pk_fma_f32 v[6:7], v[94:95], s[36:37], v[234:235] op_sel_hi:[1,0,1]
	v_pk_fma_f32 v[10:11], v[92:93], s[36:37], v[232:233] op_sel_hi:[1,0,1]
	v_pk_fma_f32 v[14:15], v[90:91], s[36:37], v[230:231] op_sel_hi:[1,0,1]
	v_pk_fma_f32 v[88:89], v[88:89], s[36:37], v[228:229] op_sel_hi:[1,0,1]
	v_pk_fma_f32 v[86:87], v[86:87], s[36:37], v[226:227] op_sel_hi:[1,0,1]
	v_pk_fma_f32 v[84:85], v[84:85], s[36:37], v[224:225] op_sel_hi:[1,0,1]
	v_pk_fma_f32 v[82:83], v[82:83], s[36:37], v[214:215] op_sel_hi:[1,0,1]
	v_pk_fma_f32 v[80:81], v[80:81], s[36:37], v[212:213] op_sel_hi:[1,0,1]
	s_cbranch_scc1 .LBB0_1007
; __device__ __forceinline__ void item_fox(const Params& p, int l, int bl, int h, int qb, LAS unsigned char* lds) {
;     ...
;         if (k0 + 63 > qw_lo) {
;             const int dq = qrow - kb0;
; #pragma unroll
;             for (int r = 0; r < 16; ++r) { const int ko = (r & 7) + 16 * (r >> 3); if (ko > dq) S0[r] = -__builtin_inff(); if (ko + 32 > dq) S1[r] = -__builtin_inff(); }
;         }
	v_cmp_gt_i32_e64 s[96:97], 22, v194
	v_cmp_gt_i32_e32 vcc, 23, v194
	v_cmp_gt_i32_e64 s[94:95], 21, v194
	v_cmp_gt_i32_e64 s[92:93], 20, v194
	v_cndmask_b32_e32 v3, v3, v208, vcc
	s_and_b64 vcc, vcc, s[96:97]
	v_cndmask_b32_e32 v2, v2, v208, vcc
	s_and_b64 vcc, vcc, s[94:95]
	v_cmp_gt_i32_e64 s[90:91], 19, v194
	v_cndmask_b32_e32 v5, v5, v208, vcc
	s_and_b64 vcc, vcc, s[92:93]
	v_cmp_gt_i32_e64 s[88:89], 18, v194
	v_cndmask_b32_e32 v4, v4, v208, vcc
	s_and_b64 vcc, vcc, s[90:91]
	v_cmp_gt_i32_e64 s[86:87], 17, v194
	v_cndmask_b32_e32 v9, v9, v208, vcc
	s_and_b64 vcc, vcc, s[88:89]
	v_cmp_gt_i32_e64 s[84:85], 16, v194
	v_cndmask_b32_e32 v8, v8, v208, vcc
	s_and_b64 vcc, vcc, s[86:87]
	v_cmp_gt_i32_e64 s[82:83], 7, v194
	v_cndmask_b32_e32 v13, v13, v208, vcc
	s_and_b64 vcc, vcc, s[84:85]
	v_cmp_gt_i32_e64 s[80:81], 6, v194
	v_cndmask_b32_e32 v12, v12, v208, vcc
	s_and_b64 vcc, vcc, s[82:83]
	v_cmp_gt_i32_e64 s[78:79], 5, v194
	v_cndmask_b32_e32 v103, v103, v208, vcc
	s_and_b64 vcc, vcc, s[80:81]
	v_cmp_gt_i32_e64 s[76:77], 4, v194
	v_cndmask_b32_e32 v102, v102, v208, vcc
	s_and_b64 vcc, vcc, s[78:79]
	v_cmp_gt_i32_e64 s[74:75], 3, v194
	v_cndmask_b32_e32 v101, v101, v208, vcc
	s_and_b64 vcc, vcc, s[76:77]
	v_cmp_gt_i32_e64 s[72:73], 2, v194
	v_cndmask_b32_e32 v100, v100, v208, vcc
	s_and_b64 vcc, vcc, s[74:75]
	v_cmp_gt_i32_e64 s[70:71], 1, v194
	v_cndmask_b32_e32 v99, v99, v208, vcc
	s_and_b64 vcc, vcc, s[72:73]
	v_cmp_gt_i32_e64 s[68:69], 0, v194
	v_cndmask_b32_e32 v98, v98, v208, vcc
	s_and_b64 vcc, vcc, s[70:71]
	v_cndmask_b32_e32 v97, v97, v208, vcc
	s_and_b64 vcc, vcc, s[68:69]
	v_cmp_gt_i32_e64 s[64:65], 54, v194
	v_cndmask_b32_e32 v96, v96, v208, vcc
	v_cmp_gt_i32_e32 vcc, 55, v194
	v_cmp_gt_i32_e64 s[62:63], 53, v194
	v_cmp_gt_i32_e64 s[60:61], 52, v194
	v_cndmask_b32_e32 v7, v7, v208, vcc
	s_and_b64 vcc, vcc, s[64:65]
	v_cndmask_b32_e32 v6, v6, v208, vcc
	s_and_b64 vcc, vcc, s[62:63]
	v_cmp_gt_i32_e64 s[58:59], 51, v194
	v_cndmask_b32_e32 v11, v11, v208, vcc
	s_and_b64 vcc, vcc, s[60:61]
	v_cmp_gt_i32_e64 s[56:57], 50, v194
	v_cndmask_b32_e32 v10, v10, v208, vcc
	s_and_b64 vcc, vcc, s[58:59]
	v_cmp_gt_i32_e64 s[54:55], 49, v194
	v_cndmask_b32_e32 v15, v15, v208, vcc
	s_and_b64 vcc, vcc, s[56:57]
	v_cmp_gt_i32_e64 s[52:53], 48, v194
	v_cndmask_b32_e32 v14, v14, v208, vcc
	s_and_b64 vcc, vcc, s[54:55]
	v_cmp_gt_i32_e64 s[50:51], 39, v194
	v_cndmask_b32_e32 v89, v89, v208, vcc
	s_and_b64 vcc, vcc, s[52:53]
	v_cmp_gt_i32_e64 s[48:49], 38, v194
	v_cndmask_b32_e32 v88, v88, v208, vcc
	s_and_b64 vcc, vcc, s[50:51]
	v_cmp_gt_i32_e64 s[46:47], 37, v194
	v_cndmask_b32_e32 v87, v87, v208, vcc
	s_and_b64 vcc, vcc, s[48:49]
	v_cmp_gt_i32_e64 s[42:43], 36, v194
	v_cndmask_b32_e32 v86, v86, v208, vcc
	s_and_b64 vcc, vcc, s[46:47]
	v_cmp_gt_i32_e64 s[40:41], 35, v194
	v_cndmask_b32_e32 v85, v85, v208, vcc
	s_and_b64 vcc, vcc, s[42:43]
	v_cmp_gt_i32_e64 s[38:39], 34, v194
	v_cndmask_b32_e32 v84, v84, v208, vcc
	s_and_b64 vcc, vcc, s[40:41]
	v_cmp_gt_i32_e64 s[0:1], 33, v194
	v_cndmask_b32_e32 v83, v83, v208, vcc
	s_and_b64 vcc, vcc, s[38:39]
	v_cmp_gt_i32_e64 s[66:67], 32, v194
	v_cndmask_b32_e32 v82, v82, v208, vcc
	s_and_b64 vcc, vcc, s[0:1]
	v_readlane_b32 s88, v253, 47
	v_cndmask_b32_e32 v81, v81, v208, vcc
	s_and_b64 vcc, vcc, s[66:67]
	s_mov_b64 s[90:91], 0x800
	v_readlane_b32 s89, v253, 48
	s_movk_i32 s87, 0x204
	s_mov_b32 s86, 0xd000
	s_mov_b32 s85, 0x800000
	s_movk_i32 s84, 0x2000
	v_readlane_b32 s82, v253, 45
	v_cndmask_b32_e32 v80, v80, v208, vcc
	v_readlane_b32 s83, v253, 46

; __device__ __forceinline__ float bflo(unsigned w) { return __uint_as_float(w << 16); }
; __device__ __forceinline__ float bfhi(unsigned w) { return __uint_as_float(w & 0xffff0000u); }
; __device__ __forceinline__ unsigned cvtpk(float lo, float hi) { unsigned r; asm volatile("v_cvt_pk_bf16_f32 %0, %1, %2" : "=v"(r) : "v"(lo), "v"(hi)); return r; }
; __device__ __forceinline__ float siluf_(float x) { return x * sigmoidf_(x); }
; __device__ __forceinline__ void item_fox(const Params& p, int l, int bl, int h, int qb, LAS unsigned char* lds) {
;     ...
;     { const float lt = lrun + __shfl_xor(lrun, 32), inv = 1.f / lt;
;       const size_t grow = (size_t)(bl * SEQ + qrow);
;       const u16* zp = p.proj + grow * NP + C_DZ + h * 128; u16* yp = p.ybuf + ((size_t)3 * MG + grow) * 512 + h * 128;
; #pragma unroll
;       for (int db = 0; db < 4; ++db)
; #pragma unroll
;           for (int r4 = 0; r4 < 4; ++r4) {
;               const int d0 = 32 * db + 8 * r4 + 4 * hi; const u32x2 z = *(const u32x2*)(zp + d0);
;               const float o0 = O[db][4 * r4] * inv * siluf_(bflo(z[0])), o1 = O[db][4 * r4 + 1] * inv * siluf_(bfhi(z[0])),
;                           o2 = O[db][4 * r4 + 2] * inv * siluf_(bflo(z[1])), o3 = O[db][4 * r4 + 3] * inv * siluf_(bfhi(z[1]));
;               u32x2 o = {cvtpk(o0, o1), cvtpk(o2, o3)}; *(u32x2*)(yp + d0) = o; } }
.LBB0_1012:
	v_cmp_lt_i32_e32 vcc, v163, v173
	s_lshl_b32 s30, s0, 1
	s_mov_b64 s[0:1], 0x3400
	v_cndmask_b32_e32 v0, v206, v163, vcc
	v_lshlrev_b32_e32 v0, 2, v0
	ds_bpermute_b32 v0, v0, v187
	v_mov_b32_e32 v10, v64
	s_waitcnt lgkmcnt(0)
	v_add_f32_e32 v0, v187, v0
	v_div_scale_f32 v2, s[20:21], v0, v0, 1.0
	v_rcp_f32_e32 v3, v2
	s_nop 0
	v_fma_f32 v4, -v2, v3, 1.0
	v_fmac_f32_e32 v3, v4, v3
	v_div_scale_f32 v4, vcc, 1.0, v0, 1.0
	v_mul_f32_e32 v5, v4, v3
	v_fma_f32 v6, -v2, v5, v4
	v_fmac_f32_e32 v5, v6, v3
	v_fma_f32 v2, -v2, v5, v4
	v_lshl_add_u32 v4, s37, 12, v161
	v_mov_b64_e32 v[6:7], s[14:15]
	v_div_fmas_f32 v2, v2, v3, v5
	v_ashrrev_i32_e32 v5, 31, v4
	v_mad_i64_i32 v[6:7], s[20:21], v4, s33, v[6:7]
	v_lshl_add_u64 v[8:9], v[6:7], 0, s[30:31]
	v_lshlrev_b64 v[4:5], 10, v[4:5]
	v_mov_b32_e32 v161, v1
	v_lshl_add_u64 v[4:5], s[16:17], 0, v[4:5]
	v_lshl_add_u64 v[8:9], v[8:9], 0, v[160:161]
	v_lshl_add_u64 v[6:7], v[4:5], 0, s[30:31]
	v_lshl_add_u64 v[4:5], v[8:9], 0, s[0:1]
	global_load_dwordx2 v[112:113], v[4:5], off
	global_load_dwordx2 v[114:115], v[4:5], off offset:16
	global_load_dwordx2 v[116:117], v[4:5], off offset:32
	global_load_dwordx2 v[118:119], v[4:5], off offset:48
	global_load_dwordx2 v[120:121], v[4:5], off offset:64
	global_load_dwordx2 v[122:123], v[4:5], off offset:80
	global_load_dwordx2 v[124:125], v[4:5], off offset:96
	global_load_dwordx2 v[126:127], v[4:5], off offset:112
	global_load_dwordx2 v[128:129], v[4:5], off offset:128
	global_load_dwordx2 v[130:131], v[4:5], off offset:144
	global_load_dwordx2 v[132:133], v[4:5], off offset:160
	global_load_dwordx2 v[134:135], v[4:5], off offset:176
	global_load_dwordx2 v[136:137], v[4:5], off offset:192
	global_load_dwordx2 v[138:139], v[4:5], off offset:208
	global_load_dwordx2 v[140:141], v[4:5], off offset:224
	global_load_dwordx2 v[142:143], v[4:5], off offset:240
	s_movk_i32 s0, 0x3000
	v_add_co_u32_e32 v8, vcc, s0, v8
	v_div_fixup_f32 v2, v2, v0, 1.0
	s_nop 0
	v_addc_co_u32_e32 v9, vcc, 0, v9, vcc
	s_waitcnt vmcnt(15)
	v_mov_b32_e32 v8, v112
	v_mov_b32_e32 v9, v113
	s_mov_b64 s[0:1], 0x3000000
	v_lshlrev_b32_e32 v3, 16, v8
	v_mul_f32_e32 v0, 0xbfb8aa3b, v3
	v_exp_f32_e32 v0, v0
	s_nop 0
	v_add_f32_e32 v0, 1.0, v0
	v_rcp_f32_e32 v11, v0
	s_nop 0
	v_pk_mul_f32 v[10:11], v[10:11], v[2:3]
	v_and_b32_e32 v3, 0xffff0000, v8
	v_mul_f32_e32 v8, 0xbfb8aa3b, v3
	v_exp_f32_e32 v8, v8
	v_mul_f32_e32 v0, v10, v11
	v_mov_b32_e32 v10, v65
	v_add_f32_e32 v8, 1.0, v8
	v_rcp_f32_e32 v11, v8
	s_nop 0
	v_pk_mul_f32 v[10:11], v[10:11], v[2:3]
	v_lshlrev_b32_e32 v3, 16, v9
	v_mul_f32_e32 v8, 0xbfb8aa3b, v3
	v_exp_f32_e32 v8, v8
	v_mul_f32_e32 v12, v10, v11
	v_mov_b32_e32 v10, v66
	v_add_f32_e32 v8, 1.0, v8
	v_rcp_f32_e32 v11, v8
	s_nop 0
	v_pk_mul_f32 v[10:11], v[10:11], v[2:3]
	v_and_b32_e32 v3, 0xffff0000, v9
	v_mul_f32_e32 v8, 0xbfb8aa3b, v3
	v_exp_f32_e32 v8, v8
	v_mul_f32_e32 v10, v10, v11
	v_add_f32_e32 v8, 1.0, v8
	v_rcp_f32_e32 v9, v8
	v_mov_b32_e32 v8, v67
	v_pk_mul_f32 v[8:9], v[8:9], v[2:3]
	s_nop 0
	v_mul_f32_e32 v3, v8, v9
	v_cvt_pk_bf16_f32 v8, v0, v12
	v_cvt_pk_bf16_f32 v9, v10, v3
	v_lshl_add_u64 v[10:11], v[6:7], 0, v[160:161]
	v_lshl_add_u64 v[6:7], v[10:11], 0, s[0:1]
	s_mov_b32 s0, 0x3000000
	v_add_co_u32_e32 v10, vcc, s0, v10
	s_mov_b64 s[0:1], -1
	s_nop 0
	v_addc_co_u32_e32 v11, vcc, 0, v11, vcc
	global_store_dwordx2 v[10:11], v[8:9], off
	s_waitcnt vmcnt(15)
	v_mov_b32_e32 v8, v114
	v_mov_b32_e32 v9, v115
	v_mov_b32_e32 v10, v68
	v_lshlrev_b32_e32 v3, 16, v8
	v_mul_f32_e32 v0, 0xbfb8aa3b, v3
	v_exp_f32_e32 v0, v0
	s_nop 0
	v_add_f32_e32 v0, 1.0, v0
	v_rcp_f32_e32 v11, v0
	s_nop 0
	v_pk_mul_f32 v[10:11], v[10:11], v[2:3]
	v_and_b32_e32 v3, 0xffff0000, v8
	v_mul_f32_e32 v8, 0xbfb8aa3b, v3
	v_exp_f32_e32 v8, v8
	v_mul_f32_e32 v0, v10, v11
	v_mov_b32_e32 v10, v69
	v_add_f32_e32 v8, 1.0, v8
	v_rcp_f32_e32 v11, v8
	s_nop 0
	v_pk_mul_f32 v[10:11], v[10:11], v[2:3]
	v_lshlrev_b32_e32 v3, 16, v9
	v_mul_f32_e32 v8, 0xbfb8aa3b, v3
	v_exp_f32_e32 v8, v8
	v_mul_f32_e32 v12, v10, v11
	v_mov_b32_e32 v10, v70
	v_add_f32_e32 v8, 1.0, v8
	v_rcp_f32_e32 v11, v8
	s_nop 0
	v_pk_mul_f32 v[10:11], v[10:11], v[2:3]
	v_and_b32_e32 v3, 0xffff0000, v9
	v_mul_f32_e32 v8, 0xbfb8aa3b, v3
	v_exp_f32_e32 v8, v8
	v_mul_f32_e32 v10, v10, v11
	v_add_f32_e32 v8, 1.0, v8
	v_rcp_f32_e32 v9, v8
	v_mov_b32_e32 v8, v71
	v_pk_mul_f32 v[8:9], v[8:9], v[2:3]
	s_nop 0
	v_mul_f32_e32 v3, v8, v9
	v_cvt_pk_bf16_f32 v8, v0, v12
	v_cvt_pk_bf16_f32 v9, v10, v3
	global_store_dwordx2 v[6:7], v[8:9], off offset:16
	s_waitcnt vmcnt(15)
	v_mov_b32_e32 v8, v116
	v_mov_b32_e32 v9, v117
	v_mov_b32_e32 v10, v72
	v_lshlrev_b32_e32 v3, 16, v8
	v_mul_f32_e32 v0, 0xbfb8aa3b, v3
	v_exp_f32_e32 v0, v0
	s_nop 0
	v_add_f32_e32 v0, 1.0, v0
	v_rcp_f32_e32 v11, v0
	s_nop 0
	v_pk_mul_f32 v[10:11], v[10:11], v[2:3]
	v_and_b32_e32 v3, 0xffff0000, v8
	v_mul_f32_e32 v8, 0xbfb8aa3b, v3
	v_exp_f32_e32 v8, v8
	v_mul_f32_e32 v0, v10, v11
	v_mov_b32_e32 v10, v73
	v_add_f32_e32 v8, 1.0, v8
	v_rcp_f32_e32 v11, v8
	s_nop 0
	v_pk_mul_f32 v[10:11], v[10:11], v[2:3]
	v_lshlrev_b32_e32 v3, 16, v9
	v_mul_f32_e32 v8, 0xbfb8aa3b, v3
	v_exp_f32_e32 v8, v8
	v_mul_f32_e32 v12, v10, v11
	v_mov_b32_e32 v10, v74
	v_add_f32_e32 v8, 1.0, v8
	v_rcp_f32_e32 v11, v8
	s_nop 0
	v_pk_mul_f32 v[10:11], v[10:11], v[2:3]
	v_and_b32_e32 v3, 0xffff0000, v9
	v_mul_f32_e32 v8, 0xbfb8aa3b, v3
	v_exp_f32_e32 v8, v8
	v_mul_f32_e32 v10, v10, v11
	v_add_f32_e32 v8, 1.0, v8
	v_rcp_f32_e32 v9, v8
	v_mov_b32_e32 v8, v75
	v_pk_mul_f32 v[8:9], v[8:9], v[2:3]
	s_nop 0
	v_mul_f32_e32 v3, v8, v9
	v_cvt_pk_bf16_f32 v8, v0, v12
	v_cvt_pk_bf16_f32 v9, v10, v3
	global_store_dwordx2 v[6:7], v[8:9], off offset:32
	s_waitcnt vmcnt(15)
; __device__ __forceinline__ float bflo(unsigned w) { return __uint_as_float(w << 16); }
; __device__ __forceinline__ float bfhi(unsigned w) { return __uint_as_float(w & 0xffff0000u); }
; __device__ __forceinline__ unsigned cvtpk(float lo, float hi) { unsigned r; asm volatile("v_cvt_pk_bf16_f32 %0, %1, %2" : "=v"(r) : "v"(lo), "v"(hi)); return r; }
; __device__ __forceinline__ float siluf_(float x) { return x * sigmoidf_(x); }
; __device__ __forceinline__ void item_fox(const Params& p, int l, int bl, int h, int qb, LAS unsigned char* lds) {
;     ...
; #pragma unroll
;       for (int db = 0; db < 4; ++db)
; #pragma unroll
;           for (int r4 = 0; r4 < 4; ++r4) {
;               const int d0 = 32 * db + 8 * r4 + 4 * hi; const u32x2 z = *(const u32x2*)(zp + d0);
;               const float o0 = O[db][4 * r4] * inv * siluf_(bflo(z[0])), o1 = O[db][4 * r4 + 1] * inv * siluf_(bfhi(z[0])),
;                           o2 = O[db][4 * r4 + 2] * inv * siluf_(bflo(z[1])), o3 = O[db][4 * r4 + 3] * inv * siluf_(bfhi(z[1]));
;               u32x2 o = {cvtpk(o0, o1), cvtpk(o2, o3)}; *(u32x2*)(yp + d0) = o; } }
	v_mov_b32_e32 v8, v118
	v_mov_b32_e32 v9, v119
	v_mov_b32_e32 v10, v76
	v_lshlrev_b32_e32 v3, 16, v8
	v_mul_f32_e32 v0, 0xbfb8aa3b, v3
	v_exp_f32_e32 v0, v0
	s_nop 0
	v_add_f32_e32 v0, 1.0, v0
	v_rcp_f32_e32 v11, v0
	s_nop 0
	v_pk_mul_f32 v[10:11], v[10:11], v[2:3]
	v_and_b32_e32 v3, 0xffff0000, v8
	v_mul_f32_e32 v8, 0xbfb8aa3b, v3
	v_exp_f32_e32 v8, v8
	v_mul_f32_e32 v0, v10, v11
	v_mov_b32_e32 v10, v77
	v_add_f32_e32 v8, 1.0, v8
	v_rcp_f32_e32 v11, v8
	s_nop 0
	v_pk_mul_f32 v[10:11], v[10:11], v[2:3]
	v_lshlrev_b32_e32 v3, 16, v9
	v_mul_f32_e32 v8, 0xbfb8aa3b, v3
	v_exp_f32_e32 v8, v8
	v_mul_f32_e32 v12, v10, v11
	v_mov_b32_e32 v10, v78
	v_add_f32_e32 v8, 1.0, v8
	v_rcp_f32_e32 v11, v8
	s_nop 0
	v_pk_mul_f32 v[10:11], v[10:11], v[2:3]
	v_and_b32_e32 v3, 0xffff0000, v9
	v_mul_f32_e32 v8, 0xbfb8aa3b, v3
	v_exp_f32_e32 v8, v8
	v_mul_f32_e32 v10, v10, v11
	v_add_f32_e32 v8, 1.0, v8
	v_rcp_f32_e32 v9, v8
	v_mov_b32_e32 v8, v79
	v_pk_mul_f32 v[8:9], v[8:9], v[2:3]
	s_nop 0
	v_mul_f32_e32 v3, v8, v9
	v_cvt_pk_bf16_f32 v8, v0, v12
	v_cvt_pk_bf16_f32 v9, v10, v3
	global_store_dwordx2 v[6:7], v[8:9], off offset:48
	s_waitcnt vmcnt(15)
	v_mov_b32_e32 v8, v120
	v_mov_b32_e32 v9, v121
	v_mov_b32_e32 v10, v48
	v_lshlrev_b32_e32 v3, 16, v8
	v_mul_f32_e32 v0, 0xbfb8aa3b, v3
	v_exp_f32_e32 v0, v0
	s_nop 0
	v_add_f32_e32 v0, 1.0, v0
	v_rcp_f32_e32 v11, v0
	s_nop 0
	v_pk_mul_f32 v[10:11], v[10:11], v[2:3]
	v_and_b32_e32 v3, 0xffff0000, v8
	v_mul_f32_e32 v8, 0xbfb8aa3b, v3
	v_exp_f32_e32 v8, v8
	v_mul_f32_e32 v0, v10, v11
	v_mov_b32_e32 v10, v49
	v_add_f32_e32 v8, 1.0, v8
	v_rcp_f32_e32 v11, v8
	s_nop 0
	v_pk_mul_f32 v[10:11], v[10:11], v[2:3]
	v_lshlrev_b32_e32 v3, 16, v9
	v_mul_f32_e32 v8, 0xbfb8aa3b, v3
	v_exp_f32_e32 v8, v8
	v_mul_f32_e32 v12, v10, v11
	v_mov_b32_e32 v10, v50
	v_add_f32_e32 v8, 1.0, v8
	v_rcp_f32_e32 v11, v8
	s_nop 0
	v_pk_mul_f32 v[10:11], v[10:11], v[2:3]
	v_and_b32_e32 v3, 0xffff0000, v9
	v_mul_f32_e32 v8, 0xbfb8aa3b, v3
	v_exp_f32_e32 v8, v8
	v_mul_f32_e32 v10, v10, v11
	v_add_f32_e32 v8, 1.0, v8
	v_rcp_f32_e32 v9, v8
	v_mov_b32_e32 v8, v51
	v_pk_mul_f32 v[8:9], v[8:9], v[2:3]
	s_nop 0
	v_mul_f32_e32 v3, v8, v9
	v_cvt_pk_bf16_f32 v8, v0, v12
	v_cvt_pk_bf16_f32 v9, v10, v3
	global_store_dwordx2 v[6:7], v[8:9], off offset:64
	s_waitcnt vmcnt(15)
	v_mov_b32_e32 v8, v122
	v_mov_b32_e32 v9, v123
	v_mov_b32_e32 v10, v52
	v_lshlrev_b32_e32 v3, 16, v8
	v_mul_f32_e32 v0, 0xbfb8aa3b, v3
	v_exp_f32_e32 v0, v0
	s_nop 0
	v_add_f32_e32 v0, 1.0, v0
	v_rcp_f32_e32 v11, v0
	s_nop 0
	v_pk_mul_f32 v[10:11], v[10:11], v[2:3]
	v_and_b32_e32 v3, 0xffff0000, v8
	v_mul_f32_e32 v8, 0xbfb8aa3b, v3
	v_exp_f32_e32 v8, v8
	v_mul_f32_e32 v0, v10, v11
	v_mov_b32_e32 v10, v53
	v_add_f32_e32 v8, 1.0, v8
	v_rcp_f32_e32 v11, v8
	s_nop 0
	v_pk_mul_f32 v[10:11], v[10:11], v[2:3]
	v_lshlrev_b32_e32 v3, 16, v9
	v_mul_f32_e32 v8, 0xbfb8aa3b, v3
	v_exp_f32_e32 v8, v8
	v_mul_f32_e32 v12, v10, v11
	v_mov_b32_e32 v10, v54
	v_add_f32_e32 v8, 1.0, v8
	v_rcp_f32_e32 v11, v8
	s_nop 0
	v_pk_mul_f32 v[10:11], v[10:11], v[2:3]
	v_and_b32_e32 v3, 0xffff0000, v9
	v_mul_f32_e32 v8, 0xbfb8aa3b, v3
	v_exp_f32_e32 v8, v8
	v_mul_f32_e32 v10, v10, v11
	v_add_f32_e32 v8, 1.0, v8
	v_rcp_f32_e32 v9, v8
	v_mov_b32_e32 v8, v55
	v_pk_mul_f32 v[8:9], v[8:9], v[2:3]
	s_nop 0
	v_mul_f32_e32 v3, v8, v9
	v_cvt_pk_bf16_f32 v8, v0, v12
	v_cvt_pk_bf16_f32 v9, v10, v3
	global_store_dwordx2 v[6:7], v[8:9], off offset:80
	s_waitcnt vmcnt(15)
	v_mov_b32_e32 v8, v124
	v_mov_b32_e32 v9, v125
	v_mov_b32_e32 v10, v56
	v_lshlrev_b32_e32 v3, 16, v8
	v_mul_f32_e32 v0, 0xbfb8aa3b, v3
	v_exp_f32_e32 v0, v0
	s_nop 0
	v_add_f32_e32 v0, 1.0, v0
	v_rcp_f32_e32 v11, v0
	s_nop 0
	v_pk_mul_f32 v[10:11], v[10:11], v[2:3]
	v_and_b32_e32 v3, 0xffff0000, v8
	v_mul_f32_e32 v8, 0xbfb8aa3b, v3
	v_exp_f32_e32 v8, v8
	v_mul_f32_e32 v0, v10, v11
	v_mov_b32_e32 v10, v57
	v_add_f32_e32 v8, 1.0, v8
	v_rcp_f32_e32 v11, v8
	s_nop 0
	v_pk_mul_f32 v[10:11], v[10:11], v[2:3]
	v_lshlrev_b32_e32 v3, 16, v9
	v_mul_f32_e32 v8, 0xbfb8aa3b, v3
	v_exp_f32_e32 v8, v8
	v_mul_f32_e32 v12, v10, v11
	v_mov_b32_e32 v10, v58
	v_add_f32_e32 v8, 1.0, v8
	v_rcp_f32_e32 v11, v8
	s_nop 0
	v_pk_mul_f32 v[10:11], v[10:11], v[2:3]
	v_and_b32_e32 v3, 0xffff0000, v9
	v_mul_f32_e32 v8, 0xbfb8aa3b, v3
	v_exp_f32_e32 v8, v8
	v_mul_f32_e32 v10, v10, v11
	v_add_f32_e32 v8, 1.0, v8
	v_rcp_f32_e32 v9, v8
	v_mov_b32_e32 v8, v59
	v_pk_mul_f32 v[8:9], v[8:9], v[2:3]
	s_nop 0
	v_mul_f32_e32 v3, v8, v9
	v_cvt_pk_bf16_f32 v8, v0, v12
	v_cvt_pk_bf16_f32 v9, v10, v3
	global_store_dwordx2 v[6:7], v[8:9], off offset:96
	s_waitcnt vmcnt(15)
	v_mov_b32_e32 v8, v126
	v_mov_b32_e32 v9, v127
	v_mov_b32_e32 v10, v60
	v_lshlrev_b32_e32 v3, 16, v8
	v_mul_f32_e32 v0, 0xbfb8aa3b, v3
	v_exp_f32_e32 v0, v0
	s_nop 0
	v_add_f32_e32 v0, 1.0, v0
	v_rcp_f32_e32 v11, v0
	s_nop 0
	v_pk_mul_f32 v[10:11], v[10:11], v[2:3]
	v_and_b32_e32 v3, 0xffff0000, v8
	v_mul_f32_e32 v8, 0xbfb8aa3b, v3
	v_exp_f32_e32 v8, v8
	v_mul_f32_e32 v0, v10, v11
	v_mov_b32_e32 v10, v61
	v_add_f32_e32 v8, 1.0, v8
	v_rcp_f32_e32 v11, v8
	s_nop 0
	v_pk_mul_f32 v[10:11], v[10:11], v[2:3]
	v_lshlrev_b32_e32 v3, 16, v9
	v_mul_f32_e32 v8, 0xbfb8aa3b, v3
	v_exp_f32_e32 v8, v8
	v_mul_f32_e32 v12, v10, v11
	v_mov_b32_e32 v10, v62
	v_add_f32_e32 v8, 1.0, v8
	v_rcp_f32_e32 v11, v8
	s_nop 0
	v_pk_mul_f32 v[10:11], v[10:11], v[2:3]
	v_and_b32_e32 v3, 0xffff0000, v9
	v_mul_f32_e32 v8, 0xbfb8aa3b, v3
	v_exp_f32_e32 v8, v8
	v_mul_f32_e32 v10, v10, v11
	v_add_f32_e32 v8, 1.0, v8
	v_rcp_f32_e32 v9, v8
	v_mov_b32_e32 v8, v63
	v_pk_mul_f32 v[8:9], v[8:9], v[2:3]
	s_nop 0
	v_mul_f32_e32 v3, v8, v9
	v_cvt_pk_bf16_f32 v8, v0, v12
	v_cvt_pk_bf16_f32 v9, v10, v3
	global_store_dwordx2 v[6:7], v[8:9], off offset:112
	s_waitcnt vmcnt(15)
; __device__ __forceinline__ float bflo(unsigned w) { return __uint_as_float(w << 16); }
; __device__ __forceinline__ float bfhi(unsigned w) { return __uint_as_float(w & 0xffff0000u); }
; __device__ __forceinline__ unsigned cvtpk(float lo, float hi) { unsigned r; asm volatile("v_cvt_pk_bf16_f32 %0, %1, %2" : "=v"(r) : "v"(lo), "v"(hi)); return r; }
; __device__ __forceinline__ float siluf_(float x) { return x * sigmoidf_(x); }
; __device__ __forceinline__ void item_fox(const Params& p, int l, int bl, int h, int qb, LAS unsigned char* lds) {
;     ...
; #pragma unroll
;       for (int db = 0; db < 4; ++db)
; #pragma unroll
;           for (int r4 = 0; r4 < 4; ++r4) {
;               const int d0 = 32 * db + 8 * r4 + 4 * hi; const u32x2 z = *(const u32x2*)(zp + d0);
;               const float o0 = O[db][4 * r4] * inv * siluf_(bflo(z[0])), o1 = O[db][4 * r4 + 1] * inv * siluf_(bfhi(z[0])),
;                           o2 = O[db][4 * r4 + 2] * inv * siluf_(bflo(z[1])), o3 = O[db][4 * r4 + 3] * inv * siluf_(bfhi(z[1]));
;               u32x2 o = {cvtpk(o0, o1), cvtpk(o2, o3)}; *(u32x2*)(yp + d0) = o; } }
	v_mov_b32_e32 v8, v128
	v_mov_b32_e32 v9, v129
	v_mov_b32_e32 v10, v32
	v_lshlrev_b32_e32 v3, 16, v8
	v_mul_f32_e32 v0, 0xbfb8aa3b, v3
	v_exp_f32_e32 v0, v0
	s_nop 0
	v_add_f32_e32 v0, 1.0, v0
	v_rcp_f32_e32 v11, v0
	s_nop 0
	v_pk_mul_f32 v[10:11], v[10:11], v[2:3]
	v_and_b32_e32 v3, 0xffff0000, v8
	v_mul_f32_e32 v8, 0xbfb8aa3b, v3
	v_exp_f32_e32 v8, v8
	v_mul_f32_e32 v0, v10, v11
	v_mov_b32_e32 v10, v33
	v_add_f32_e32 v8, 1.0, v8
	v_rcp_f32_e32 v11, v8
	s_nop 0
	v_pk_mul_f32 v[10:11], v[10:11], v[2:3]
	v_lshlrev_b32_e32 v3, 16, v9
	v_mul_f32_e32 v8, 0xbfb8aa3b, v3
	v_exp_f32_e32 v8, v8
	v_mul_f32_e32 v12, v10, v11
	v_mov_b32_e32 v10, v34
	v_add_f32_e32 v8, 1.0, v8
	v_rcp_f32_e32 v11, v8
	s_nop 0
	v_pk_mul_f32 v[10:11], v[10:11], v[2:3]
	v_and_b32_e32 v3, 0xffff0000, v9
	v_mul_f32_e32 v8, 0xbfb8aa3b, v3
	v_exp_f32_e32 v8, v8
	v_mul_f32_e32 v10, v10, v11
	v_add_f32_e32 v8, 1.0, v8
	v_rcp_f32_e32 v9, v8
	v_mov_b32_e32 v8, v35
	v_pk_mul_f32 v[8:9], v[8:9], v[2:3]
	s_nop 0
	v_mul_f32_e32 v3, v8, v9
	v_cvt_pk_bf16_f32 v8, v0, v12
	v_cvt_pk_bf16_f32 v9, v10, v3
	global_store_dwordx2 v[6:7], v[8:9], off offset:128
	s_waitcnt vmcnt(15)
	v_mov_b32_e32 v8, v130
	v_mov_b32_e32 v9, v131
	v_mov_b32_e32 v10, v36
	v_lshlrev_b32_e32 v3, 16, v8
	v_mul_f32_e32 v0, 0xbfb8aa3b, v3
	v_exp_f32_e32 v0, v0
	s_nop 0
	v_add_f32_e32 v0, 1.0, v0
	v_rcp_f32_e32 v11, v0
	s_nop 0
	v_pk_mul_f32 v[10:11], v[10:11], v[2:3]
	v_and_b32_e32 v3, 0xffff0000, v8
	v_mul_f32_e32 v8, 0xbfb8aa3b, v3
	v_exp_f32_e32 v8, v8
	v_mul_f32_e32 v0, v10, v11
	v_mov_b32_e32 v10, v37
	v_add_f32_e32 v8, 1.0, v8
	v_rcp_f32_e32 v11, v8
	s_nop 0
	v_pk_mul_f32 v[10:11], v[10:11], v[2:3]
	v_lshlrev_b32_e32 v3, 16, v9
	v_mul_f32_e32 v8, 0xbfb8aa3b, v3
	v_exp_f32_e32 v8, v8
	v_mul_f32_e32 v12, v10, v11
	v_mov_b32_e32 v10, v38
	v_add_f32_e32 v8, 1.0, v8
	v_rcp_f32_e32 v11, v8
	s_nop 0
	v_pk_mul_f32 v[10:11], v[10:11], v[2:3]
	v_and_b32_e32 v3, 0xffff0000, v9
	v_mul_f32_e32 v8, 0xbfb8aa3b, v3
	v_exp_f32_e32 v8, v8
	v_mul_f32_e32 v10, v10, v11
	v_add_f32_e32 v8, 1.0, v8
	v_rcp_f32_e32 v9, v8
	v_mov_b32_e32 v8, v39
	v_pk_mul_f32 v[8:9], v[8:9], v[2:3]
	s_nop 0
	v_mul_f32_e32 v3, v8, v9
	v_cvt_pk_bf16_f32 v8, v0, v12
	v_cvt_pk_bf16_f32 v9, v10, v3
	global_store_dwordx2 v[6:7], v[8:9], off offset:144
	s_waitcnt vmcnt(15)
	v_mov_b32_e32 v8, v132
	v_mov_b32_e32 v9, v133
	v_mov_b32_e32 v10, v40
	v_lshlrev_b32_e32 v3, 16, v8
	v_mul_f32_e32 v0, 0xbfb8aa3b, v3
	v_exp_f32_e32 v0, v0
	s_nop 0
	v_add_f32_e32 v0, 1.0, v0
	v_rcp_f32_e32 v11, v0
	s_nop 0
	v_pk_mul_f32 v[10:11], v[10:11], v[2:3]
	v_and_b32_e32 v3, 0xffff0000, v8
	v_mul_f32_e32 v8, 0xbfb8aa3b, v3
	v_exp_f32_e32 v8, v8
	v_mul_f32_e32 v0, v10, v11
	v_mov_b32_e32 v10, v41
	v_add_f32_e32 v8, 1.0, v8
	v_rcp_f32_e32 v11, v8
	s_nop 0
	v_pk_mul_f32 v[10:11], v[10:11], v[2:3]
	v_lshlrev_b32_e32 v3, 16, v9
	v_mul_f32_e32 v8, 0xbfb8aa3b, v3
	v_exp_f32_e32 v8, v8
	v_mul_f32_e32 v12, v10, v11
	v_mov_b32_e32 v10, v42
	v_add_f32_e32 v8, 1.0, v8
	v_rcp_f32_e32 v11, v8
	s_nop 0
	v_pk_mul_f32 v[10:11], v[10:11], v[2:3]
	v_and_b32_e32 v3, 0xffff0000, v9
	v_mul_f32_e32 v8, 0xbfb8aa3b, v3
	v_exp_f32_e32 v8, v8
	v_mul_f32_e32 v10, v10, v11
	v_add_f32_e32 v8, 1.0, v8
	v_rcp_f32_e32 v9, v8
	v_mov_b32_e32 v8, v43
	v_pk_mul_f32 v[8:9], v[8:9], v[2:3]
	s_nop 0
	v_mul_f32_e32 v3, v8, v9
	v_cvt_pk_bf16_f32 v8, v0, v12
	v_cvt_pk_bf16_f32 v9, v10, v3
	global_store_dwordx2 v[6:7], v[8:9], off offset:160
	s_waitcnt vmcnt(15)
	v_mov_b32_e32 v8, v134
	v_mov_b32_e32 v9, v135
	v_mov_b32_e32 v10, v44
	v_lshlrev_b32_e32 v3, 16, v8
	v_mul_f32_e32 v0, 0xbfb8aa3b, v3
	v_exp_f32_e32 v0, v0
	s_nop 0
	v_add_f32_e32 v0, 1.0, v0
	v_rcp_f32_e32 v11, v0
	s_nop 0
	v_pk_mul_f32 v[10:11], v[10:11], v[2:3]
	v_and_b32_e32 v3, 0xffff0000, v8
	v_mul_f32_e32 v8, 0xbfb8aa3b, v3
	v_exp_f32_e32 v8, v8
	v_mul_f32_e32 v0, v10, v11
	v_mov_b32_e32 v10, v45
	v_add_f32_e32 v8, 1.0, v8
	v_rcp_f32_e32 v11, v8
	s_nop 0
	v_pk_mul_f32 v[10:11], v[10:11], v[2:3]
	v_lshlrev_b32_e32 v3, 16, v9
	v_mul_f32_e32 v8, 0xbfb8aa3b, v3
	v_exp_f32_e32 v8, v8
	v_mul_f32_e32 v12, v10, v11
	v_mov_b32_e32 v10, v46
	v_add_f32_e32 v8, 1.0, v8
	v_rcp_f32_e32 v11, v8
	s_nop 0
	v_pk_mul_f32 v[10:11], v[10:11], v[2:3]
	v_and_b32_e32 v3, 0xffff0000, v9
	v_mul_f32_e32 v8, 0xbfb8aa3b, v3
	v_exp_f32_e32 v8, v8
	v_mul_f32_e32 v10, v10, v11
	v_add_f32_e32 v8, 1.0, v8
	v_rcp_f32_e32 v9, v8
	v_mov_b32_e32 v8, v47
	v_pk_mul_f32 v[8:9], v[8:9], v[2:3]
	s_nop 0
	v_mul_f32_e32 v3, v8, v9
	v_cvt_pk_bf16_f32 v8, v0, v12
	v_cvt_pk_bf16_f32 v9, v10, v3
	global_store_dwordx2 v[6:7], v[8:9], off offset:176
	s_waitcnt vmcnt(15)
; __device__ __forceinline__ float bflo(unsigned w) { return __uint_as_float(w << 16); }
; __device__ __forceinline__ float bfhi(unsigned w) { return __uint_as_float(w & 0xffff0000u); }
; __device__ __forceinline__ unsigned cvtpk(float lo, float hi) { unsigned r; asm volatile("v_cvt_pk_bf16_f32 %0, %1, %2" : "=v"(r) : "v"(lo), "v"(hi)); return r; }
; __device__ __forceinline__ float siluf_(float x) { return x * sigmoidf_(x); }
; __device__ __forceinline__ void item_fox(const Params& p, int l, int bl, int h, int qb, LAS unsigned char* lds) {
;     ...
; #pragma unroll
;       for (int db = 0; db < 4; ++db)
; #pragma unroll
;           for (int r4 = 0; r4 < 4; ++r4) {
;               const int d0 = 32 * db + 8 * r4 + 4 * hi; const u32x2 z = *(const u32x2*)(zp + d0);
;               const float o0 = O[db][4 * r4] * inv * siluf_(bflo(z[0])), o1 = O[db][4 * r4 + 1] * inv * siluf_(bfhi(z[0])),
;                           o2 = O[db][4 * r4 + 2] * inv * siluf_(bflo(z[1])), o3 = O[db][4 * r4 + 3] * inv * siluf_(bfhi(z[1]));
;               u32x2 o = {cvtpk(o0, o1), cvtpk(o2, o3)}; *(u32x2*)(yp + d0) = o; } }
;     __syncthreads();
	v_mov_b32_e32 v8, v136
	v_mov_b32_e32 v9, v137
	v_mov_b32_e32 v10, v16
	v_lshlrev_b32_e32 v3, 16, v8
	v_mul_f32_e32 v0, 0xbfb8aa3b, v3
	v_exp_f32_e32 v0, v0
	s_nop 0
	v_add_f32_e32 v0, 1.0, v0
	v_rcp_f32_e32 v11, v0
	s_nop 0
	v_pk_mul_f32 v[10:11], v[10:11], v[2:3]
	v_and_b32_e32 v3, 0xffff0000, v8
	v_mul_f32_e32 v8, 0xbfb8aa3b, v3
	v_exp_f32_e32 v8, v8
	v_mul_f32_e32 v0, v10, v11
	v_mov_b32_e32 v10, v17
	v_add_f32_e32 v8, 1.0, v8
	v_rcp_f32_e32 v11, v8
	s_nop 0
	v_pk_mul_f32 v[10:11], v[10:11], v[2:3]
	v_lshlrev_b32_e32 v3, 16, v9
	v_mul_f32_e32 v8, 0xbfb8aa3b, v3
	v_exp_f32_e32 v8, v8
	v_mul_f32_e32 v12, v10, v11
	v_mov_b32_e32 v10, v18
	v_add_f32_e32 v8, 1.0, v8
	v_rcp_f32_e32 v11, v8
	s_nop 0
	v_pk_mul_f32 v[10:11], v[10:11], v[2:3]
	v_and_b32_e32 v3, 0xffff0000, v9
	v_mul_f32_e32 v8, 0xbfb8aa3b, v3
	v_exp_f32_e32 v8, v8
	v_mul_f32_e32 v10, v10, v11
	v_add_f32_e32 v8, 1.0, v8
	v_rcp_f32_e32 v9, v8
	v_mov_b32_e32 v8, v19
	v_pk_mul_f32 v[8:9], v[8:9], v[2:3]
	s_nop 0
	v_mul_f32_e32 v3, v8, v9
	v_cvt_pk_bf16_f32 v8, v0, v12
	v_cvt_pk_bf16_f32 v9, v10, v3
	global_store_dwordx2 v[6:7], v[8:9], off offset:192
	s_waitcnt vmcnt(15)
	v_mov_b32_e32 v8, v138
	v_mov_b32_e32 v9, v139
	v_mov_b32_e32 v10, v20
	v_lshlrev_b32_e32 v3, 16, v8
	v_mul_f32_e32 v0, 0xbfb8aa3b, v3
	v_exp_f32_e32 v0, v0
	s_nop 0
	v_add_f32_e32 v0, 1.0, v0
	v_rcp_f32_e32 v11, v0
	s_nop 0
	v_pk_mul_f32 v[10:11], v[10:11], v[2:3]
	v_and_b32_e32 v3, 0xffff0000, v8
	v_mul_f32_e32 v8, 0xbfb8aa3b, v3
	v_exp_f32_e32 v8, v8
	v_mul_f32_e32 v0, v10, v11
	v_mov_b32_e32 v10, v21
	v_add_f32_e32 v8, 1.0, v8
	v_rcp_f32_e32 v11, v8
	s_nop 0
	v_pk_mul_f32 v[10:11], v[10:11], v[2:3]
	v_lshlrev_b32_e32 v3, 16, v9
	v_mul_f32_e32 v8, 0xbfb8aa3b, v3
	v_exp_f32_e32 v8, v8
	v_mul_f32_e32 v12, v10, v11
	v_mov_b32_e32 v10, v22
	v_add_f32_e32 v8, 1.0, v8
	v_rcp_f32_e32 v11, v8
	s_nop 0
	v_pk_mul_f32 v[10:11], v[10:11], v[2:3]
	v_and_b32_e32 v3, 0xffff0000, v9
	v_mul_f32_e32 v8, 0xbfb8aa3b, v3
	v_exp_f32_e32 v8, v8
	v_mul_f32_e32 v10, v10, v11
	v_add_f32_e32 v8, 1.0, v8
	v_rcp_f32_e32 v9, v8
	v_mov_b32_e32 v8, v23
	v_pk_mul_f32 v[8:9], v[8:9], v[2:3]
	s_nop 0
	v_mul_f32_e32 v3, v8, v9
	v_cvt_pk_bf16_f32 v8, v0, v12
	v_cvt_pk_bf16_f32 v9, v10, v3
	global_store_dwordx2 v[6:7], v[8:9], off offset:208
	s_waitcnt vmcnt(15)
	v_mov_b32_e32 v8, v140
	v_mov_b32_e32 v9, v141
	v_mov_b32_e32 v10, v24
	v_lshlrev_b32_e32 v3, 16, v8
	v_mul_f32_e32 v0, 0xbfb8aa3b, v3
	v_exp_f32_e32 v0, v0
	s_nop 0
	v_add_f32_e32 v0, 1.0, v0
	v_rcp_f32_e32 v11, v0
	s_nop 0
	v_pk_mul_f32 v[10:11], v[10:11], v[2:3]
	v_and_b32_e32 v3, 0xffff0000, v8
	v_mul_f32_e32 v8, 0xbfb8aa3b, v3
	v_exp_f32_e32 v8, v8
	v_mul_f32_e32 v0, v10, v11
	v_mov_b32_e32 v10, v25
	v_add_f32_e32 v8, 1.0, v8
	v_rcp_f32_e32 v11, v8
	s_nop 0
	v_pk_mul_f32 v[10:11], v[10:11], v[2:3]
	v_lshlrev_b32_e32 v3, 16, v9
	v_mul_f32_e32 v8, 0xbfb8aa3b, v3
	v_exp_f32_e32 v8, v8
	v_mul_f32_e32 v12, v10, v11
	v_mov_b32_e32 v10, v26
	v_add_f32_e32 v8, 1.0, v8
	v_rcp_f32_e32 v11, v8
	s_nop 0
	v_pk_mul_f32 v[10:11], v[10:11], v[2:3]
	v_and_b32_e32 v3, 0xffff0000, v9
	v_mul_f32_e32 v8, 0xbfb8aa3b, v3
	v_exp_f32_e32 v8, v8
	v_mul_f32_e32 v10, v10, v11
	v_add_f32_e32 v8, 1.0, v8
	v_rcp_f32_e32 v9, v8
	v_mov_b32_e32 v8, v27
	v_pk_mul_f32 v[8:9], v[8:9], v[2:3]
	s_nop 0
	v_mul_f32_e32 v3, v8, v9
	v_cvt_pk_bf16_f32 v8, v0, v12
	v_cvt_pk_bf16_f32 v9, v10, v3
	global_store_dwordx2 v[6:7], v[8:9], off offset:224
	s_waitcnt vmcnt(15)
	v_mov_b32_e32 v4, v142
	v_mov_b32_e32 v5, v143
	v_mov_b32_e32 v8, v28
	v_lshlrev_b32_e32 v3, 16, v4
	v_mul_f32_e32 v0, 0xbfb8aa3b, v3
	v_exp_f32_e32 v0, v0
	s_nop 0
	v_add_f32_e32 v0, 1.0, v0
	v_rcp_f32_e32 v9, v0
	s_nop 0
	v_pk_mul_f32 v[8:9], v[8:9], v[2:3]
	v_and_b32_e32 v3, 0xffff0000, v4
	v_mul_f32_e32 v4, 0xbfb8aa3b, v3
	v_exp_f32_e32 v4, v4
	v_mul_f32_e32 v0, v8, v9
	v_mov_b32_e32 v8, v29
	v_add_f32_e32 v4, 1.0, v4
	v_rcp_f32_e32 v9, v4
	s_nop 0
	v_pk_mul_f32 v[8:9], v[8:9], v[2:3]
	v_lshlrev_b32_e32 v3, 16, v5
	v_mul_f32_e32 v4, 0xbfb8aa3b, v3
	v_exp_f32_e32 v4, v4
	v_mul_f32_e32 v10, v8, v9
	v_mov_b32_e32 v8, v30
	v_add_f32_e32 v4, 1.0, v4
	v_rcp_f32_e32 v9, v4
	s_nop 0
	v_pk_mul_f32 v[8:9], v[8:9], v[2:3]
	v_and_b32_e32 v3, 0xffff0000, v5
	v_mul_f32_e32 v4, 0xbfb8aa3b, v3
	v_exp_f32_e32 v4, v4
	v_mul_f32_e32 v8, v8, v9
	v_add_f32_e32 v4, 1.0, v4
	v_rcp_f32_e32 v5, v4
	v_mov_b32_e32 v4, v31
	v_pk_mul_f32 v[2:3], v[4:5], v[2:3]
	s_nop 0
	v_mul_f32_e32 v3, v2, v3
	v_cvt_pk_bf16_f32 v2, v0, v10
	v_cvt_pk_bf16_f32 v3, v8, v3
	global_store_dwordx2 v[6:7], v[2:3], off offset:240
	s_barrier

; #define LAS __attribute__((address_space(3)))
; __device__ __forceinline__ unsigned cvtpk(float lo, float hi) { unsigned r; asm volatile("v_cvt_pk_bf16_f32 %0, %1, %2" : "=v"(r) : "v"(lo), "v"(hi)); return r; }
; __device__ __forceinline__ int opq(int x) { asm volatile("" : "+v"(x)); return x; }
; __device__ __forceinline__ void tr_tile(const float* src, int ldS, u16* dst, int ldD, int n0, int k0, bool wmap, const float* rs, LAS float* tile) {
;     const int tid = opq(threadIdx.x);
;     { const int nn = tid & 63, kr = tid >> 6; int sc = n0 + nn; if (wmap) sc = win_src(sc);
; #pragma unroll
;       for (int i = 0; i < 8; ++i) { const int k = kr + 8 * i; float v = 0.f; if (sc >= 0) { v = src[(size_t)(k0 + k) * ldS + sc]; if (rs) v *= rs[k0 + k]; } tile[k * 65 + nn] = v; } }
;     __syncthreads();
;     { const int kk = (tid & 31) * 2, nr = tid >> 5;
; #pragma unroll
;       for (int i = 0; i < 4; ++i) { const int n = nr + 16 * i; *(unsigned*)(dst + (size_t)(n0 + n) * ldD + k0 + kk) = cvtpk(tile[kk * 65 + n], tile[(kk + 1) * 65 + n]); } }
;     __syncthreads();
; }
.LBB0_1169:
	s_or_b64 exec, exec, s[0:1]
	s_lshl_b32 s0, s37, 4
	s_sub_i32 s0, s29, s0
	s_lshl_b32 s0, s0, 6
	v_ashrrev_i32_e32 v12, 6, v10
	v_cmp_lt_i32_e32 vcc, -1, v0
	v_lshl_add_u64 v[8:9], v[0:1], 2, s[48:49]
	v_mov_b32_e32 v30, 0
	v_mov_b32_e32 v31, 0
	v_mov_b32_e32 v32, 0
	v_mov_b32_e32 v33, 0
	v_mov_b32_e32 v34, 0
	v_mov_b32_e32 v35, 0
	v_mov_b32_e32 v36, 0
	v_mov_b32_e32 v37, 0
	s_and_saveexec_b64 s[20:21], vcc
	s_cbranch_execz .Lprep_ld_done
	v_add_u32_e32 v0, s0, v12
	s_mov_b32 s1, 0xaf20
	v_mad_i64_i32 v[14:15], s[22:23], v0, s1, v[8:9]
	s_mov_b64 s[22:23], 0x57900
	global_load_dword v30, v[14:15], off
	v_lshl_add_u64 v[14:15], v[14:15], 0, s[22:23]
	global_load_dword v31, v[14:15], off
	v_lshl_add_u64 v[14:15], v[14:15], 0, s[22:23]
	global_load_dword v32, v[14:15], off
	v_lshl_add_u64 v[14:15], v[14:15], 0, s[22:23]
	global_load_dword v33, v[14:15], off
	v_lshl_add_u64 v[14:15], v[14:15], 0, s[22:23]
	global_load_dword v34, v[14:15], off
	v_lshl_add_u64 v[14:15], v[14:15], 0, s[22:23]
	global_load_dword v35, v[14:15], off
	v_lshl_add_u64 v[14:15], v[14:15], 0, s[22:23]
	global_load_dword v36, v[14:15], off
	v_lshl_add_u64 v[14:15], v[14:15], 0, s[22:23]
	global_load_dword v37, v[14:15], off
.Lprep_ld_done:
	s_or_b64 exec, exec, s[20:21]
	s_movk_i32 s1, 0x104
	v_lshl_add_u32 v0, v11, 2, 0
	v_mul_lo_u32 v11, v12, s1
	v_add_u32_e32 v0, v0, v11
	s_waitcnt vmcnt(0)
	ds_write_b32 v0, v30
	ds_write_b32 v0, v31 offset:2080
	ds_write_b32 v0, v32 offset:4160
	ds_write_b32 v0, v33 offset:6240
	ds_write_b32 v0, v34 offset:8320
	ds_write_b32 v0, v35 offset:10400
	ds_write_b32 v0, v36 offset:12480
	ds_write_b32 v0, v37 offset:14560
	v_lshlrev_b32_e32 v0, 1, v10
	v_and_b32_e32 v0, 62, v0
	v_ashrrev_i32_e32 v12, 5, v10
	s_ashr_i32 s1, s0, 31
	v_mul_u32_u24_e32 v8, 0x104, v0
	s_lshl_b64 s[0:1], s[0:1], 1
	v_lshlrev_b32_e32 v9, 2, v12
	v_add3_u32 v20, 0, v8, v9
	s_add_u32 s0, s4, s0
	s_waitcnt lgkmcnt(0)
	s_barrier
	ds_read2_b32 v[8:9], v20 offset1:65
	s_addc_u32 s1, s5, s1
	v_lshlrev_b32_e32 v0, 1, v0
	v_lshl_add_u64 v[10:11], s[0:1], 0, v[0:1]
	s_waitcnt lgkmcnt(0)
	v_cvt_pk_bf16_f32 v0, v8, v9
	v_add_u32_e32 v8, s30, v12
	v_ashrrev_i32_e32 v9, 31, v8
	v_lshlrev_b64 v[14:15], 11, v[8:9]
	ds_read2_b32 v[12:13], v20 offset0:16 offset1:81
	v_lshl_add_u64 v[14:15], v[10:11], 0, v[14:15]
	global_store_dword v[14:15], v0, off
	s_waitcnt lgkmcnt(0)
	v_cvt_pk_bf16_f32 v0, v12, v13
	v_add_u32_e32 v12, 16, v8
	v_ashrrev_i32_e32 v13, 31, v12
	v_lshlrev_b64 v[12:13], 11, v[12:13]
	v_lshl_add_u64 v[12:13], v[10:11], 0, v[12:13]
	global_store_dword v[12:13], v0, off
	v_add_u32_e32 v12, 32, v8
	v_add_u32_e32 v8, 48, v8
	v_ashrrev_i32_e32 v13, 31, v12
	v_ashrrev_i32_e32 v9, 31, v8
	v_lshlrev_b64 v[12:13], 11, v[12:13]
	v_lshlrev_b64 v[8:9], 11, v[8:9]
	ds_read2_b32 v[14:15], v20 offset0:32 offset1:97
	s_waitcnt lgkmcnt(0)
	v_cvt_pk_bf16_f32 v0, v14, v15
	v_lshl_add_u64 v[12:13], v[10:11], 0, v[12:13]
	v_lshl_add_u64 v[8:9], v[10:11], 0, v[8:9]
	s_mov_b64 s[0:1], -1
	ds_read2_b32 v[14:15], v20 offset0:48 offset1:113
	global_store_dword v[12:13], v0, off
	s_waitcnt lgkmcnt(0)
	v_cvt_pk_bf16_f32 v0, v14, v15
	global_store_dword v[8:9], v0, off
	s_barrier

; __device__ __forceinline__ unsigned cvtpk(float lo, float hi) { unsigned r; asm volatile("v_cvt_pk_bf16_f32 %0, %1, %2" : "=v"(r) : "v"(lo), "v"(hi)); return r; }
; __device__ __forceinline__ int opq(int x) { asm volatile("" : "+v"(x)); return x; }
; __device__ __forceinline__ float wave_sum(float v) { for (int o = 32; o >= 1; o >>= 1) v += __shfl_xor(v, o); return v; }
; __device__ __forceinline__ void step_norm(const Params& p, int l, int g) {
;     const float* src = (l == 0) ? p.x : p.out; const float* gw = p.norm_g + l * DM;
;     const int tidq = opq(threadIdx.x), wid = tidq >> 6, lane = tidq & 63, gwv = blockIdx.x * 8 + wid, nwv = gridDim.x * 8;
;     for (int r = gwv; r < MG; r += nwv) {
;         const float* xr = src + (size_t)(g * MG + r) * DM; f32x4 v[4]; float ss = 0.f;
; #pragma unroll
;         for (int i = 0; i < 4; ++i) { v[i] = *(const f32x4*)(xr + lane * 4 + 256 * i); ss += v[i][0] * v[i][0] + v[i][1] * v[i][1] + v[i][2] * v[i][2] + v[i][3] * v[i][3]; }
;         ss = wave_sum(ss); const float rstd = rsqrtf(ss * (1.f / DM) + EPS);
; #pragma unroll
;         for (int i = 0; i < 4; ++i) { const f32x4 gv = *(const f32x4*)(gw + lane * 4 + 256 * i);
;             u32x2 o = {cvtpk(v[i][0] * rstd * gv[0], v[i][1] * rstd * gv[1]), cvtpk(v[i][2] * rstd * gv[2], v[i][3] * rstd * gv[3])};
;             *(u32x2*)(p.hbuf + (size_t)r * DM + lane * 4 + 256 * i) = o; }
.LBB0_1189:
	v_mov_b32_e32 v3, v198
	v_readlane_b32 s0, v251, 40
	v_ashrrev_i32_e32 v0, 6, v3
	s_nop 0
	v_add_u32_e32 v2, s0, v0
	s_movk_i32 s0, 0x4000
	v_cmp_gt_i32_e32 vcc, s0, v2
	s_and_saveexec_b64 s[0:1], vcc
	s_cbranch_execz .LBB0_1192
	v_and_b32_e32 v0, 64, v206
	v_add_u32_e32 v0, 64, v0
	v_xor_b32_e32 v4, 32, v206
	v_cmp_lt_i32_e32 vcc, v4, v0
	v_readlane_b32 s22, v251, 11
	v_readlane_b32 s23, v251, 12
	v_cndmask_b32_e32 v4, v206, v4, vcc
	v_lshlrev_b32_e32 v10, 2, v4
	v_xor_b32_e32 v4, 16, v206
	s_load_dword s20, s[22:23], 0x10
	s_nop 0
	s_load_dword s22, s[22:23], 0x0
	v_cmp_lt_i32_e32 vcc, v4, v0
	v_readlane_b32 s40, v253, 3
	v_readlane_b32 s44, v253, 7
	v_cndmask_b32_e32 v4, v206, v4, vcc
	v_lshlrev_b32_e32 v11, 2, v4
	v_xor_b32_e32 v4, 8, v206
	v_cmp_lt_i32_e32 vcc, v4, v0
	s_waitcnt lgkmcnt(0)
	s_lshr_b32 s20, s20, 16
	s_cmp_lg_u32 s20, 0
	v_cndmask_b32_e32 v4, v206, v4, vcc
	v_lshlrev_b32_e32 v12, 2, v4
	v_xor_b32_e32 v4, 4, v206
	s_cselect_b64 s[20:21], -1, 0
	v_cmp_lt_i32_e32 vcc, v4, v0
	s_cmp_lg_u64 s[20:21], 0
	s_addc_u32 s20, s22, 0
	v_cndmask_b32_e32 v4, v206, v4, vcc
	v_readlane_b32 s22, v251, 15
	v_readlane_b32 s45, v253, 8
	v_readlane_b32 s46, v253, 9
	v_readlane_b32 s47, v253, 10
	v_readlane_b32 s48, v253, 11
	v_readlane_b32 s49, v253, 12
	v_readlane_b32 s50, v253, 13
	v_readlane_b32 s51, v253, 14
	v_readlane_b32 s52, v253, 15
	v_readlane_b32 s53, v253, 16
	v_readlane_b32 s54, v253, 17
	v_readlane_b32 s55, v253, 18
	v_lshlrev_b32_e32 v13, 2, v4
	v_xor_b32_e32 v4, 2, v206
	s_add_i32 s21, s22, 9
	s_lshl_b32 s20, s20, 3
	v_readlane_b32 s44, v253, 22
	v_cmp_lt_i32_e32 vcc, v4, v0
	v_readlane_b32 s23, v251, 16
	s_cmp_lt_u32 s21, 19
	v_readlane_b32 s41, v253, 4
	v_readlane_b32 s58, v253, 36
	v_readlane_b32 s59, v253, 37
	v_readlane_b32 s24, v253, 49
	v_cndmask_b32_e32 v4, v206, v4, vcc
	s_cselect_b32 s23, s41, s59
	s_cselect_b32 s22, s40, s58
	v_readlane_b32 s25, v253, 50
	s_lshl_b32 s24, s24, 10
	v_lshlrev_b32_e32 v14, 2, v4
	v_xor_b32_e32 v4, 1, v206
	s_ashr_i32 s25, s24, 31
	v_cmp_lt_i32_e32 vcc, v4, v0
	v_readlane_b32 s42, v253, 5
	s_lshl_b64 s[24:25], s[24:25], 2
	v_cndmask_b32_e32 v0, v206, v4, vcc
	v_readlane_b32 s21, v253, 51
	v_readlane_b32 s43, v253, 6
	s_add_u32 s24, s42, s24
	v_lshlrev_b32_e32 v15, 2, v0
	v_lshlrev_b32_e32 v0, 4, v3
	v_lshl_add_u32 v6, s21, 14, v2
	s_addc_u32 s25, s43, s25
	v_and_b32_e32 v0, 0x3f0, v0
	v_ashrrev_i32_e32 v7, 31, v6
	v_lshl_add_u64 v[4:5], s[24:25], 0, v[0:1]
	v_lshlrev_b64 v[6:7], 12, v[6:7]
	v_and_b32_e32 v0, 63, v3
	v_ashrrev_i32_e32 v3, 31, v2
	v_lshl_or_b32 v6, v0, 4, v6
	v_lshlrev_b64 v[8:9], 11, v[2:3]
	v_readlane_b32 s24, v253, 20
	v_lshl_add_u64 v[6:7], s[22:23], 0, v[6:7]
	s_ashr_i32 s21, s20, 31
	v_lshl_or_b32 v8, v0, 3, v8
	v_readlane_b32 s25, v253, 21
	v_lshl_add_u64 v[6:7], v[6:7], 0, s[90:91]
	s_lshl_b64 s[22:23], s[20:21], 12
	v_lshl_add_u64 v[8:9], s[24:25], 0, v[8:9]
	s_lshl_b64 s[24:25], s[20:21], 11
	s_mov_b64 s[26:27], 0
	v_readlane_b32 s45, v253, 23
	v_readlane_b32 s46, v253, 24
	v_readlane_b32 s47, v253, 25
	v_readlane_b32 s48, v253, 26
	v_readlane_b32 s49, v253, 27
	v_readlane_b32 s50, v253, 28
	v_readlane_b32 s51, v253, 29
	v_readlane_b32 s52, v253, 30
	v_readlane_b32 s53, v253, 31
	v_readlane_b32 s54, v253, 32
	v_readlane_b32 s55, v253, 33
	v_readlane_b32 s56, v253, 34
	v_readlane_b32 s57, v253, 35
	global_load_dwordx4 v[32:35], v[4:5], off
	global_load_dwordx4 v[52:55], v[4:5], off offset:1024
	global_load_dwordx4 v[56:59], v[4:5], off offset:2048
	global_load_dwordx4 v[60:63], v[4:5], off offset:3072
	global_load_dwordx4 v[16:19], v[6:7], off offset:-2048
	global_load_dwordx4 v[20:23], v[6:7], off offset:-1024
	global_load_dwordx4 v[24:27], v[6:7], off
	global_load_dwordx4 v[28:31], v[6:7], off offset:1024
	s_waitcnt vmcnt(0)
; __device__ __forceinline__ unsigned cvtpk(float lo, float hi) { unsigned r; asm volatile("v_cvt_pk_bf16_f32 %0, %1, %2" : "=v"(r) : "v"(lo), "v"(hi)); return r; }
; __device__ __forceinline__ float wave_sum(float v) { for (int o = 32; o >= 1; o >>= 1) v += __shfl_xor(v, o); return v; }
; __device__ __forceinline__ void step_norm(const Params& p, int l, int g) {
;     ...
;     for (int r = gwv; r < MG; r += nwv) {
;         const float* xr = src + (size_t)(g * MG + r) * DM; f32x4 v[4]; float ss = 0.f;
; #pragma unroll
;         for (int i = 0; i < 4; ++i) { v[i] = *(const f32x4*)(xr + lane * 4 + 256 * i); ss += v[i][0] * v[i][0] + v[i][1] * v[i][1] + v[i][2] * v[i][2] + v[i][3] * v[i][3]; }
;         ss = wave_sum(ss); const float rstd = rsqrtf(ss * (1.f / DM) + EPS);
; #pragma unroll
;         for (int i = 0; i < 4; ++i) { const f32x4 gv = *(const f32x4*)(gw + lane * 4 + 256 * i);
;             u32x2 o = {cvtpk(v[i][0] * rstd * gv[0], v[i][1] * rstd * gv[1]), cvtpk(v[i][2] * rstd * gv[2], v[i][3] * rstd * gv[3])};
;             *(u32x2*)(p.hbuf + (size_t)r * DM + lane * 4 + 256 * i) = o; }
;     }
.Lnrm_loop_A:
	v_add_u32_e32 v2, s20, v2
	v_cmp_gt_i32_e32 vcc, 0x4000, v2
	v_lshl_add_u64 v[6:7], v[6:7], 0, s[22:23]
	s_mov_b64 s[26:27], vcc
	s_cbranch_vccz .Lnrm_np_A
	global_load_dwordx4 v[64:67], v[6:7], off offset:-2048
	global_load_dwordx4 v[68:71], v[6:7], off offset:-1024
	global_load_dwordx4 v[72:75], v[6:7], off
	global_load_dwordx4 v[76:79], v[6:7], off offset:1024
	s_waitcnt vmcnt(8)
	s_branch .Lnrm_go_A
.Lnrm_np_A:
	s_waitcnt vmcnt(4)
.Lnrm_go_A:
	v_mov_b32_e32 v38, v17
	v_mov_b32_e32 v39, v21
	v_mov_b32_e32 v36, v16
	v_mov_b32_e32 v37, v20
	v_mov_b32_e32 v46, v25
	v_mov_b32_e32 v47, v29
	v_pk_mul_f32 v[38:39], v[38:39], v[38:39]
	v_mov_b32_e32 v40, v18
	v_mov_b32_e32 v41, v22
	v_mov_b32_e32 v44, v24
	v_mov_b32_e32 v45, v28
	v_pk_mul_f32 v[46:47], v[46:47], v[46:47]
	v_pk_fma_f32 v[36:37], v[36:37], v[36:37], v[38:39]
	v_mov_b32_e32 v42, v19
	v_mov_b32_e32 v43, v23
	v_mov_b32_e32 v48, v26
	v_mov_b32_e32 v49, v30
	v_pk_fma_f32 v[38:39], v[44:45], v[44:45], v[46:47]
	v_pk_fma_f32 v[36:37], v[40:41], v[40:41], v[36:37]
	v_mov_b32_e32 v50, v27
	v_mov_b32_e32 v51, v31
	v_pk_fma_f32 v[38:39], v[48:49], v[48:49], v[38:39]
	v_pk_fma_f32 v[36:37], v[42:43], v[42:43], v[36:37]
	v_pk_fma_f32 v[38:39], v[50:51], v[50:51], v[38:39]
	v_add_f32_e32 v0, v36, v37
	v_add_f32_e32 v0, v0, v38
	v_add_f32_e32 v0, v0, v39
	ds_bpermute_b32 v3, v10, v0
	s_waitcnt lgkmcnt(0)
	v_add_f32_e32 v0, v0, v3
	ds_bpermute_b32 v3, v11, v0
	s_waitcnt lgkmcnt(0)
	v_add_f32_e32 v0, v0, v3
	ds_bpermute_b32 v3, v12, v0
	s_waitcnt lgkmcnt(0)
	v_add_f32_e32 v0, v0, v3
	ds_bpermute_b32 v3, v13, v0
	s_waitcnt lgkmcnt(0)
	v_add_f32_e32 v0, v0, v3
	ds_bpermute_b32 v3, v14, v0
	s_waitcnt lgkmcnt(0)
	v_add_f32_e32 v0, v0, v3
	ds_bpermute_b32 v3, v15, v0
	s_waitcnt lgkmcnt(0)
	v_add_f32_e32 v0, v0, v3
	v_fmamk_f32 v0, v0, 0x3a800000, v199
	v_mul_f32_e32 v3, 0x4b800000, v0
	v_cmp_gt_f32_e32 vcc, s85, v0
	s_nop 1
	v_cndmask_b32_e32 v0, v0, v3, vcc
	v_rsq_f32_e32 v0, v0
	s_nop 0
	v_mul_f32_e32 v3, 0x45800000, v0
	v_cndmask_b32_e32 v0, v0, v3, vcc
	v_mul_f32_e32 v40, v16, v0
	v_mul_f32_e32 v41, v17, v0
	v_mul_f32_e32 v42, v18, v0
	v_mul_f32_e32 v43, v19, v0
	v_mul_f32_e32 v40, v32, v40
	v_mul_f32_e32 v41, v33, v41
	v_mul_f32_e32 v42, v34, v42
	v_mul_f32_e32 v43, v35, v43
	v_cvt_pk_bf16_f32 v48, v40, v41
	v_cvt_pk_bf16_f32 v49, v42, v43
	global_store_dwordx2 v[8:9], v[48:49], off offset:-1024
	v_mul_f32_e32 v44, v20, v0
	v_mul_f32_e32 v45, v21, v0
	v_mul_f32_e32 v46, v22, v0
	v_mul_f32_e32 v47, v23, v0
	v_mul_f32_e32 v44, v52, v44
	v_mul_f32_e32 v45, v53, v45
	v_mul_f32_e32 v46, v54, v46
	v_mul_f32_e32 v47, v55, v47
	v_cvt_pk_bf16_f32 v50, v44, v45
	v_cvt_pk_bf16_f32 v51, v46, v47
	global_store_dwordx2 v[8:9], v[50:51], off offset:-512
	v_mul_f32_e32 v40, v24, v0
	v_mul_f32_e32 v41, v25, v0
	v_mul_f32_e32 v42, v26, v0
	v_mul_f32_e32 v43, v27, v0
	v_mul_f32_e32 v40, v56, v40
	v_mul_f32_e32 v41, v57, v41
	v_mul_f32_e32 v42, v58, v42
	v_mul_f32_e32 v43, v59, v43
	v_cvt_pk_bf16_f32 v48, v40, v41
	v_cvt_pk_bf16_f32 v49, v42, v43
	global_store_dwordx2 v[8:9], v[48:49], off
	v_mul_f32_e32 v44, v28, v0
	v_mul_f32_e32 v45, v29, v0
	v_mul_f32_e32 v46, v30, v0
	v_mul_f32_e32 v47, v31, v0
	v_mul_f32_e32 v44, v60, v44
	v_mul_f32_e32 v45, v61, v45
	v_mul_f32_e32 v46, v62, v46
	v_mul_f32_e32 v47, v63, v47
	v_cvt_pk_bf16_f32 v50, v44, v45
	v_cvt_pk_bf16_f32 v51, v46, v47
	global_store_dwordx2 v[8:9], v[50:51], off offset:512
	v_lshl_add_u64 v[8:9], v[8:9], 0, s[24:25]
	s_and_b64 vcc, exec, s[26:27]
	s_cbranch_vccz .Lnrm_done
.Lnrm_loop_B:
	v_add_u32_e32 v2, s20, v2
	v_cmp_gt_i32_e32 vcc, 0x4000, v2
	v_lshl_add_u64 v[6:7], v[6:7], 0, s[22:23]
	s_mov_b64 s[26:27], vcc
	s_cbranch_vccz .Lnrm_np_B
	global_load_dwordx4 v[16:19], v[6:7], off offset:-2048
	global_load_dwordx4 v[20:23], v[6:7], off offset:-1024
	global_load_dwordx4 v[24:27], v[6:7], off
	global_load_dwordx4 v[28:31], v[6:7], off offset:1024
	s_waitcnt vmcnt(8)
	s_branch .Lnrm_go_B

; __device__ __forceinline__ unsigned cvtpk(float lo, float hi) { unsigned r; asm volatile("v_cvt_pk_bf16_f32 %0, %1, %2" : "=v"(r) : "v"(lo), "v"(hi)); return r; }
; __device__ __forceinline__ float wave_sum(float v) { for (int o = 32; o >= 1; o >>= 1) v += __shfl_xor(v, o); return v; }
; __device__ __forceinline__ void step_norm(const Params& p, int l, int g) {
;     ...
;         const float* xr = src + (size_t)(g * MG + r) * DM; f32x4 v[4]; float ss = 0.f;
; #pragma unroll
;         for (int i = 0; i < 4; ++i) { v[i] = *(const f32x4*)(xr + lane * 4 + 256 * i); ss += v[i][0] * v[i][0] + v[i][1] * v[i][1] + v[i][2] * v[i][2] + v[i][3] * v[i][3]; }
;         ss = wave_sum(ss); const float rstd = rsqrtf(ss * (1.f / DM) + EPS);
; #pragma unroll
;         for (int i = 0; i < 4; ++i) { const f32x4 gv = *(const f32x4*)(gw + lane * 4 + 256 * i);
;             u32x2 o = {cvtpk(v[i][0] * rstd * gv[0], v[i][1] * rstd * gv[1]), cvtpk(v[i][2] * rstd * gv[2], v[i][3] * rstd * gv[3])};
;             *(u32x2*)(p.hbuf + (size_t)r * DM + lane * 4 + 256 * i) = o; }
;     }
.Lnrm_go_B:
	v_mov_b32_e32 v38, v65
	v_mov_b32_e32 v39, v69
	v_mov_b32_e32 v36, v64
	v_mov_b32_e32 v37, v68
	v_mov_b32_e32 v46, v73
	v_mov_b32_e32 v47, v77
	v_pk_mul_f32 v[38:39], v[38:39], v[38:39]
	v_mov_b32_e32 v40, v66
	v_mov_b32_e32 v41, v70
	v_mov_b32_e32 v44, v72
	v_mov_b32_e32 v45, v76
	v_pk_mul_f32 v[46:47], v[46:47], v[46:47]
	v_pk_fma_f32 v[36:37], v[36:37], v[36:37], v[38:39]
	v_mov_b32_e32 v42, v67
	v_mov_b32_e32 v43, v71
	v_mov_b32_e32 v48, v74
	v_mov_b32_e32 v49, v78
	v_pk_fma_f32 v[38:39], v[44:45], v[44:45], v[46:47]
	v_pk_fma_f32 v[36:37], v[40:41], v[40:41], v[36:37]
	v_mov_b32_e32 v50, v75
	v_mov_b32_e32 v51, v79
	v_pk_fma_f32 v[38:39], v[48:49], v[48:49], v[38:39]
	v_pk_fma_f32 v[36:37], v[42:43], v[42:43], v[36:37]
	v_pk_fma_f32 v[38:39], v[50:51], v[50:51], v[38:39]
	v_add_f32_e32 v0, v36, v37
	v_add_f32_e32 v0, v0, v38
	v_add_f32_e32 v0, v0, v39
	ds_bpermute_b32 v3, v10, v0
	s_waitcnt lgkmcnt(0)
	v_add_f32_e32 v0, v0, v3
	ds_bpermute_b32 v3, v11, v0
	s_waitcnt lgkmcnt(0)
	v_add_f32_e32 v0, v0, v3
	ds_bpermute_b32 v3, v12, v0
	s_waitcnt lgkmcnt(0)
	v_add_f32_e32 v0, v0, v3
	ds_bpermute_b32 v3, v13, v0
	s_waitcnt lgkmcnt(0)
	v_add_f32_e32 v0, v0, v3
	ds_bpermute_b32 v3, v14, v0
	s_waitcnt lgkmcnt(0)
	v_add_f32_e32 v0, v0, v3
	ds_bpermute_b32 v3, v15, v0
	s_waitcnt lgkmcnt(0)
	v_add_f32_e32 v0, v0, v3
	v_fmamk_f32 v0, v0, 0x3a800000, v199
	v_mul_f32_e32 v3, 0x4b800000, v0
	v_cmp_gt_f32_e32 vcc, s85, v0
	s_nop 1
	v_cndmask_b32_e32 v0, v0, v3, vcc
	v_rsq_f32_e32 v0, v0
	s_nop 0
	v_mul_f32_e32 v3, 0x45800000, v0
	v_cndmask_b32_e32 v0, v0, v3, vcc
	v_mul_f32_e32 v40, v64, v0
	v_mul_f32_e32 v41, v65, v0
	v_mul_f32_e32 v42, v66, v0
	v_mul_f32_e32 v43, v67, v0
	v_mul_f32_e32 v40, v32, v40
	v_mul_f32_e32 v41, v33, v41
	v_mul_f32_e32 v42, v34, v42
	v_mul_f32_e32 v43, v35, v43
	v_cvt_pk_bf16_f32 v48, v40, v41
	v_cvt_pk_bf16_f32 v49, v42, v43
	global_store_dwordx2 v[8:9], v[48:49], off offset:-1024
	v_mul_f32_e32 v44, v68, v0
	v_mul_f32_e32 v45, v69, v0
	v_mul_f32_e32 v46, v70, v0
	v_mul_f32_e32 v47, v71, v0
	v_mul_f32_e32 v44, v52, v44
	v_mul_f32_e32 v45, v53, v45
	v_mul_f32_e32 v46, v54, v46
	v_mul_f32_e32 v47, v55, v47
	v_cvt_pk_bf16_f32 v50, v44, v45
	v_cvt_pk_bf16_f32 v51, v46, v47
	global_store_dwordx2 v[8:9], v[50:51], off offset:-512
	v_mul_f32_e32 v40, v72, v0
	v_mul_f32_e32 v41, v73, v0
	v_mul_f32_e32 v42, v74, v0
	v_mul_f32_e32 v43, v75, v0
	v_mul_f32_e32 v40, v56, v40
	v_mul_f32_e32 v41, v57, v41
	v_mul_f32_e32 v42, v58, v42
	v_mul_f32_e32 v43, v59, v43
	v_cvt_pk_bf16_f32 v48, v40, v41
	v_cvt_pk_bf16_f32 v49, v42, v43
	global_store_dwordx2 v[8:9], v[48:49], off
	v_mul_f32_e32 v44, v76, v0
	v_mul_f32_e32 v45, v77, v0
	v_mul_f32_e32 v46, v78, v0
	v_mul_f32_e32 v47, v79, v0
	v_mul_f32_e32 v44, v60, v44
	v_mul_f32_e32 v45, v61, v45
	v_mul_f32_e32 v46, v62, v46
	v_mul_f32_e32 v47, v63, v47
	v_cvt_pk_bf16_f32 v50, v44, v45
	v_cvt_pk_bf16_f32 v51, v46, v47
	global_store_dwordx2 v[8:9], v[50:51], off offset:512
	v_lshl_add_u64 v[8:9], v[8:9], 0, s[24:25]
	s_and_b64 vcc, exec, s[26:27]
	s_cbranch_vccnz .Lnrm_loop_A
.Lnrm_done:
.LBB0_1192:
	s_or_b64 exec, exec, s[0:1]

; __device__ __forceinline__ int opq(int x) { asm volatile("" : "+v"(x)); return x; }
; __device__ __forceinline__ float wave_sum(float v) { for (int o = 32; o >= 1; o >>= 1) v += __shfl_xor(v, o); return v; }
; __device__ __forceinline__ void step_final(const Params& p) {
;     const int tidq = opq(threadIdx.x), wid = tidq >> 6, lane = tidq & 63, gwv = blockIdx.x * 8 + wid, nwv = gridDim.x * 8;
;     for (int r = gwv; r < 32768; r += nwv) {
;         float* xr = p.out + (size_t)r * DM; f32x4 v[4]; float ss = 0.f;
; #pragma unroll
;         for (int i = 0; i < 4; ++i) { v[i] = *(const f32x4*)(xr + lane * 4 + 256 * i); ss += v[i][0] * v[i][0] + v[i][1] * v[i][1] + v[i][2] * v[i][2] + v[i][3] * v[i][3]; }
;         ss = wave_sum(ss); const float rstd = rsqrtf(ss * (1.f / DM) + EPS);
; #pragma unroll
;         for (int i = 0; i < 4; ++i) { const f32x4 gv = *(const f32x4*)(p.final_g + lane * 4 + 256 * i); *(f32x4*)(xr + lane * 4 + 256 * i) = v[i] * rstd * gv; }
.LBB0_1194:
	s_and_b64 vcc, exec, s[0:1]
	s_cbranch_vccz .LBB0_1199
	v_mov_b32_e32 v6, v198
	v_readlane_b32 s0, v251, 40
	v_ashrrev_i32_e32 v0, 6, v6
	s_nop 0
	v_add_u32_e32 v2, s0, v0
	s_mov_b32 s0, 0x8000
	v_cmp_gt_i32_e32 vcc, s0, v2
	s_and_saveexec_b64 s[0:1], vcc
	s_cbranch_execz .LBB0_1198
	v_and_b32_e32 v0, 64, v206
	v_add_u32_e32 v0, 64, v0
	v_xor_b32_e32 v3, 32, v206
	v_cmp_lt_i32_e32 vcc, v3, v0
	v_readlane_b32 s40, v253, 22
	v_readlane_b32 s52, v253, 34
	v_cndmask_b32_e32 v3, v206, v3, vcc
	v_lshlrev_b32_e32 v8, 2, v3
	v_xor_b32_e32 v3, 16, v206
	v_cmp_lt_i32_e32 vcc, v3, v0
	v_readlane_b32 s53, v253, 35
	v_readlane_b32 s20, v253, 38
	v_cndmask_b32_e32 v3, v206, v3, vcc
	v_lshlrev_b32_e32 v9, 2, v3
	v_xor_b32_e32 v3, 8, v206
	v_cmp_lt_i32_e32 vcc, v3, v0
	v_readlane_b32 s21, v253, 39
	v_readlane_b32 s41, v253, 23
	v_cndmask_b32_e32 v3, v206, v3, vcc
	v_lshlrev_b32_e32 v10, 2, v3
	v_xor_b32_e32 v3, 4, v206
	v_cmp_lt_i32_e32 vcc, v3, v0
	v_readlane_b32 s42, v253, 24
	v_readlane_b32 s43, v253, 25
	v_cndmask_b32_e32 v3, v206, v3, vcc
	v_lshlrev_b32_e32 v11, 2, v3
	v_xor_b32_e32 v3, 2, v206
	v_cmp_lt_i32_e32 vcc, v3, v0
	v_readlane_b32 s44, v253, 26
	v_readlane_b32 s45, v253, 27
	v_cndmask_b32_e32 v3, v206, v3, vcc
	v_lshlrev_b32_e32 v12, 2, v3
	v_xor_b32_e32 v3, 1, v206
	v_cmp_lt_i32_e32 vcc, v3, v0
	v_readlane_b32 s46, v253, 28
	v_readlane_b32 s47, v253, 29
	v_cndmask_b32_e32 v0, v206, v3, vcc
	v_lshlrev_b32_e32 v13, 2, v0
	v_lshlrev_b32_e32 v0, 4, v6
	v_and_b32_e32 v0, 0x3f0, v0
	v_ashrrev_i32_e32 v3, 31, v2
	v_lshl_add_u64 v[4:5], s[52:53], 0, v[0:1]
	v_lshlrev_b64 v[14:15], 12, v[2:3]
	v_and_b32_e32 v0, 63, v6
	v_lshl_or_b32 v14, v0, 4, v14
	v_lshl_add_u64 v[6:7], s[20:21], 0, v[14:15]
	s_mov_b64 s[20:21], 0
	v_readlane_b32 s48, v253, 30
	v_readlane_b32 s49, v253, 31
	v_readlane_b32 s50, v253, 32
	v_readlane_b32 s51, v253, 33
	v_readlane_b32 s54, v253, 36
	v_readlane_b32 s55, v253, 37
	global_load_dwordx4 v[32:35], v[4:5], off
	global_load_dwordx4 v[52:55], v[4:5], off offset:1024
	global_load_dwordx4 v[56:59], v[4:5], off offset:2048
	global_load_dwordx4 v[60:63], v[4:5], off offset:3072
	global_load_dwordx4 v[16:19], v[6:7], off offset:-3072
	global_load_dwordx4 v[20:23], v[6:7], off offset:-2048
	global_load_dwordx4 v[24:27], v[6:7], off offset:-1024
	global_load_dwordx4 v[28:31], v[6:7], off
	s_waitcnt vmcnt(0)
.Lfin_loop_A:
	v_add_u32_e32 v2, s82, v2
	v_cmp_gt_i32_e32 vcc, 0x8000, v2
	v_lshl_add_u64 v[80:81], v[6:7], 0, s[88:89]
	s_mov_b64 s[20:21], vcc
	s_cbranch_vccz .Lfin_np_A
	global_load_dwordx4 v[64:67], v[80:81], off offset:-3072
	global_load_dwordx4 v[68:71], v[80:81], off offset:-2048
	global_load_dwordx4 v[72:75], v[80:81], off offset:-1024
	global_load_dwordx4 v[76:79], v[80:81], off
	s_waitcnt vmcnt(8)
	s_branch .Lfin_go_A

; __device__ __forceinline__ float wave_sum(float v) { for (int o = 32; o >= 1; o >>= 1) v += __shfl_xor(v, o); return v; }
; __device__ __forceinline__ void step_final(const Params& p) {
;     ...
;         float* xr = p.out + (size_t)r * DM; f32x4 v[4]; float ss = 0.f;
; #pragma unroll
;         for (int i = 0; i < 4; ++i) { v[i] = *(const f32x4*)(xr + lane * 4 + 256 * i); ss += v[i][0] * v[i][0] + v[i][1] * v[i][1] + v[i][2] * v[i][2] + v[i][3] * v[i][3]; }
;         ss = wave_sum(ss); const float rstd = rsqrtf(ss * (1.f / DM) + EPS);
; #pragma unroll
;         for (int i = 0; i < 4; ++i) { const f32x4 gv = *(const f32x4*)(p.final_g + lane * 4 + 256 * i); *(f32x4*)(xr + lane * 4 + 256 * i) = v[i] * rstd * gv; }
;     }
.Lfin_go_A:
	v_mov_b32_e32 v38, v17
	v_mov_b32_e32 v39, v21
	v_mov_b32_e32 v36, v16
	v_mov_b32_e32 v37, v20
	v_mov_b32_e32 v46, v25
	v_mov_b32_e32 v47, v29
	v_pk_mul_f32 v[38:39], v[38:39], v[38:39]
	v_mov_b32_e32 v40, v18
	v_mov_b32_e32 v41, v22
	v_mov_b32_e32 v44, v24
	v_mov_b32_e32 v45, v28
	v_pk_mul_f32 v[46:47], v[46:47], v[46:47]
	v_pk_fma_f32 v[36:37], v[36:37], v[36:37], v[38:39]
	v_mov_b32_e32 v42, v19
	v_mov_b32_e32 v43, v23
	v_mov_b32_e32 v48, v26
	v_mov_b32_e32 v49, v30
	v_pk_fma_f32 v[38:39], v[44:45], v[44:45], v[46:47]
	v_pk_fma_f32 v[36:37], v[40:41], v[40:41], v[36:37]
	v_mov_b32_e32 v50, v27
	v_mov_b32_e32 v51, v31
	v_pk_fma_f32 v[38:39], v[48:49], v[48:49], v[38:39]
	v_pk_fma_f32 v[36:37], v[42:43], v[42:43], v[36:37]
	v_pk_fma_f32 v[38:39], v[50:51], v[50:51], v[38:39]
	v_add_f32_e32 v0, v36, v37
	v_add_f32_e32 v0, v0, v38
	v_add_f32_e32 v0, v0, v39
	ds_bpermute_b32 v3, v8, v0
	s_waitcnt lgkmcnt(0)
	v_add_f32_e32 v0, v0, v3
	ds_bpermute_b32 v3, v9, v0
	s_waitcnt lgkmcnt(0)
	v_add_f32_e32 v0, v0, v3
	ds_bpermute_b32 v3, v10, v0
	s_waitcnt lgkmcnt(0)
	v_add_f32_e32 v0, v0, v3
	ds_bpermute_b32 v3, v11, v0
	s_waitcnt lgkmcnt(0)
	v_add_f32_e32 v0, v0, v3
	ds_bpermute_b32 v3, v12, v0
	s_waitcnt lgkmcnt(0)
	v_add_f32_e32 v0, v0, v3
	ds_bpermute_b32 v3, v13, v0
	s_waitcnt lgkmcnt(0)
	v_add_f32_e32 v0, v0, v3
	v_fmamk_f32 v0, v0, 0x3a800000, v199
	v_mul_f32_e32 v3, 0x4b800000, v0
	v_cmp_gt_f32_e32 vcc, s85, v0
	s_nop 1
	v_cndmask_b32_e32 v0, v0, v3, vcc
	v_rsq_f32_e32 v0, v0
	s_nop 0
	v_mul_f32_e32 v3, 0x45800000, v0
	v_cndmask_b32_e32 v0, v0, v3, vcc
	v_mul_f32_e32 v40, v16, v0
	v_mul_f32_e32 v41, v17, v0
	v_mul_f32_e32 v42, v18, v0
	v_mul_f32_e32 v43, v19, v0
	v_mul_f32_e32 v40, v32, v40
	v_mul_f32_e32 v41, v33, v41
	v_mul_f32_e32 v42, v34, v42
	v_mul_f32_e32 v43, v35, v43
	global_store_dwordx4 v[6:7], v[40:43], off offset:-3072
	v_mul_f32_e32 v44, v20, v0
	v_mul_f32_e32 v45, v21, v0
	v_mul_f32_e32 v46, v22, v0
	v_mul_f32_e32 v47, v23, v0
	v_mul_f32_e32 v44, v52, v44
	v_mul_f32_e32 v45, v53, v45
	v_mul_f32_e32 v46, v54, v46
	v_mul_f32_e32 v47, v55, v47
	global_store_dwordx4 v[6:7], v[44:47], off offset:-2048
	v_mul_f32_e32 v40, v24, v0
	v_mul_f32_e32 v41, v25, v0
	v_mul_f32_e32 v42, v26, v0
	v_mul_f32_e32 v43, v27, v0
	v_mul_f32_e32 v40, v56, v40
	v_mul_f32_e32 v41, v57, v41
	v_mul_f32_e32 v42, v58, v42
	v_mul_f32_e32 v43, v59, v43
	global_store_dwordx4 v[6:7], v[40:43], off offset:-1024
	v_mul_f32_e32 v44, v28, v0
	v_mul_f32_e32 v45, v29, v0
	v_mul_f32_e32 v46, v30, v0
	v_mul_f32_e32 v47, v31, v0
	v_mul_f32_e32 v44, v60, v44
	v_mul_f32_e32 v45, v61, v45
	v_mul_f32_e32 v46, v62, v46
	v_mul_f32_e32 v47, v63, v47
	global_store_dwordx4 v[6:7], v[44:47], off
	v_mov_b32_e32 v6, v80
	v_mov_b32_e32 v7, v81
	s_and_b64 vcc, exec, s[20:21]
	s_cbranch_vccz .Lfin_done
.Lfin_loop_B:
	v_add_u32_e32 v2, s82, v2
	v_cmp_gt_i32_e32 vcc, 0x8000, v2
	v_lshl_add_u64 v[80:81], v[6:7], 0, s[88:89]
	s_mov_b64 s[20:21], vcc
	s_cbranch_vccz .Lfin_np_B
	global_load_dwordx4 v[16:19], v[80:81], off offset:-3072
	global_load_dwordx4 v[20:23], v[80:81], off offset:-2048
	global_load_dwordx4 v[24:27], v[80:81], off offset:-1024
	global_load_dwordx4 v[28:31], v[80:81], off
	s_waitcnt vmcnt(8)
	s_branch .Lfin_go_B

; __device__ __forceinline__ float wave_sum(float v) { for (int o = 32; o >= 1; o >>= 1) v += __shfl_xor(v, o); return v; }
; __device__ __forceinline__ void step_final(const Params& p) {
;     ...
;         float* xr = p.out + (size_t)r * DM; f32x4 v[4]; float ss = 0.f;
; #pragma unroll
;         for (int i = 0; i < 4; ++i) { v[i] = *(const f32x4*)(xr + lane * 4 + 256 * i); ss += v[i][0] * v[i][0] + v[i][1] * v[i][1] + v[i][2] * v[i][2] + v[i][3] * v[i][3]; }
;         ss = wave_sum(ss); const float rstd = rsqrtf(ss * (1.f / DM) + EPS);
; #pragma unroll
;         for (int i = 0; i < 4; ++i) { const f32x4 gv = *(const f32x4*)(p.final_g + lane * 4 + 256 * i); *(f32x4*)(xr + lane * 4 + 256 * i) = v[i] * rstd * gv; }
;     }
.Lfin_go_B:
	v_mov_b32_e32 v38, v65
	v_mov_b32_e32 v39, v69
	v_mov_b32_e32 v36, v64
	v_mov_b32_e32 v37, v68
	v_mov_b32_e32 v46, v73
	v_mov_b32_e32 v47, v77
	v_pk_mul_f32 v[38:39], v[38:39], v[38:39]
	v_mov_b32_e32 v40, v66
	v_mov_b32_e32 v41, v70
	v_mov_b32_e32 v44, v72
	v_mov_b32_e32 v45, v76
	v_pk_mul_f32 v[46:47], v[46:47], v[46:47]
	v_pk_fma_f32 v[36:37], v[36:37], v[36:37], v[38:39]
	v_mov_b32_e32 v42, v67
	v_mov_b32_e32 v43, v71
	v_mov_b32_e32 v48, v74
	v_mov_b32_e32 v49, v78
	v_pk_fma_f32 v[38:39], v[44:45], v[44:45], v[46:47]
	v_pk_fma_f32 v[36:37], v[40:41], v[40:41], v[36:37]
	v_mov_b32_e32 v50, v75
	v_mov_b32_e32 v51, v79
	v_pk_fma_f32 v[38:39], v[48:49], v[48:49], v[38:39]
	v_pk_fma_f32 v[36:37], v[42:43], v[42:43], v[36:37]
	v_pk_fma_f32 v[38:39], v[50:51], v[50:51], v[38:39]
	v_add_f32_e32 v0, v36, v37
	v_add_f32_e32 v0, v0, v38
	v_add_f32_e32 v0, v0, v39
	ds_bpermute_b32 v3, v8, v0
	s_waitcnt lgkmcnt(0)
	v_add_f32_e32 v0, v0, v3
	ds_bpermute_b32 v3, v9, v0
	s_waitcnt lgkmcnt(0)
	v_add_f32_e32 v0, v0, v3
	ds_bpermute_b32 v3, v10, v0
	s_waitcnt lgkmcnt(0)
	v_add_f32_e32 v0, v0, v3
	ds_bpermute_b32 v3, v11, v0
	s_waitcnt lgkmcnt(0)
	v_add_f32_e32 v0, v0, v3
	ds_bpermute_b32 v3, v12, v0
	s_waitcnt lgkmcnt(0)
	v_add_f32_e32 v0, v0, v3
	ds_bpermute_b32 v3, v13, v0
	s_waitcnt lgkmcnt(0)
	v_add_f32_e32 v0, v0, v3
	v_fmamk_f32 v0, v0, 0x3a800000, v199
	v_mul_f32_e32 v3, 0x4b800000, v0
	v_cmp_gt_f32_e32 vcc, s85, v0
	s_nop 1
	v_cndmask_b32_e32 v0, v0, v3, vcc
	v_rsq_f32_e32 v0, v0
	s_nop 0
	v_mul_f32_e32 v3, 0x45800000, v0
	v_cndmask_b32_e32 v0, v0, v3, vcc
	v_mul_f32_e32 v40, v64, v0
	v_mul_f32_e32 v41, v65, v0
	v_mul_f32_e32 v42, v66, v0
	v_mul_f32_e32 v43, v67, v0
	v_mul_f32_e32 v40, v32, v40
	v_mul_f32_e32 v41, v33, v41
	v_mul_f32_e32 v42, v34, v42
	v_mul_f32_e32 v43, v35, v43
	global_store_dwordx4 v[6:7], v[40:43], off offset:-3072
	v_mul_f32_e32 v44, v68, v0
	v_mul_f32_e32 v45, v69, v0
	v_mul_f32_e32 v46, v70, v0
	v_mul_f32_e32 v47, v71, v0
	v_mul_f32_e32 v44, v52, v44
	v_mul_f32_e32 v45, v53, v45
	v_mul_f32_e32 v46, v54, v46
	v_mul_f32_e32 v47, v55, v47
	global_store_dwordx4 v[6:7], v[44:47], off offset:-2048
	v_mul_f32_e32 v40, v72, v0
	v_mul_f32_e32 v41, v73, v0
	v_mul_f32_e32 v42, v74, v0
	v_mul_f32_e32 v43, v75, v0
	v_mul_f32_e32 v40, v56, v40
	v_mul_f32_e32 v41, v57, v41
	v_mul_f32_e32 v42, v58, v42
	v_mul_f32_e32 v43, v59, v43
	global_store_dwordx4 v[6:7], v[40:43], off offset:-1024
	v_mul_f32_e32 v44, v76, v0
	v_mul_f32_e32 v45, v77, v0
	v_mul_f32_e32 v46, v78, v0
	v_mul_f32_e32 v47, v79, v0
	v_mul_f32_e32 v44, v60, v44
	v_mul_f32_e32 v45, v61, v45
	v_mul_f32_e32 v46, v62, v46
	v_mul_f32_e32 v47, v63, v47
	global_store_dwordx4 v[6:7], v[44:47], off
	v_mov_b32_e32 v6, v80
	v_mov_b32_e32 v7, v81
	s_and_b64 vcc, exec, s[20:21]
	s_cbranch_vccnz .Lfin_loop_A
